# instruction selection: silu/sigmoid prelude in the IN and UP epilogues packed (pairs of v_mul_f32 by -log2e and of +1.0 adds -> v_pk_mul_f32 / v_pk_add_f32, same IEEE results); on top of v59
# speedup vs baseline: 1.0050x; 1.0037x over previous
;     __device__ __forceinline__ void operator()(f32x4 (&acc)[2][2][4][2], const pg8::Unit& u, int ui, int wr, int wc, int fr, int fq) const {
;         const int b = u.pm >> 4, grp = u.pn >> 2;
;         const int row0 = u.pm * 256 + wr * 64 + fr, colt = (u.pn & 3) * 256 + wc * 32 + fq * 8, gcol = u.pn * 256 + wc * 32 + fq * 8;
;         f32x4 sw[2][2], lb[2][2];
; #pragma unroll
;         for (int bj = 0; bj < 2; ++bj)
; #pragma unroll
;             for (int n = 0; n < 2; ++n) { sw[bj][n] = *(const f32x4*)(SW + (size_t)b * DIN + gcol + bj * 128 + n * 4); lb[bj][n] = (grp == 1) ? *(const f32x4*)(LBl + colt + bj * 128 + n * 4) : (f32x4){0.f, 0.f, 0.f, 0.f}; }
.LBB0_331:
	s_mov_b32 s100, 0xbfb8aa3b
	v_mbcnt_lo_u32_b32 v176, -1, 0
	v_mbcnt_hi_u32_b32 v176, -1, v176
	s_lshl_b32 s7, s41, 8
	v_ashrrev_i32_e32 v10, 1, v176
	s_ashr_i32 s6, s8, 4
	s_and_b32 s31, s7, 0x300
	v_and_b32_e32 v14, -8, v10
	s_or_b32 s7, s7, s81
	s_ashr_i32 s29, s41, 2
	s_or_b32 s31, s31, s81
	v_add_u32_e32 v10, s7, v14
	s_mul_hi_i32 s7, s6, 0x5000
	s_mulk_i32 s6, 0x5000
	s_add_u32 s6, s70, s6
	s_addc_u32 s7, s83, s7
	v_ashrrev_i32_e32 v11, 31, v10
	v_lshl_add_u64 v[12:13], v[10:11], 2, s[6:7]
	global_load_dwordx4 v[50:53], v[12:13], off
	v_add_u32_e32 v172, s31, v14
	s_cmp_eq_u32 s29, 1
	v_ashrrev_i32_e32 v173, 31, v172
	s_cselect_b64 s[86:87], -1, 0
	s_cmp_lg_u32 s29, 1
	v_lshl_add_u64 v[174:175], v[172:173], 2, s[18:19]
	v_mov_b32_e32 v26, 0
	v_mov_b32_e32 v38, 0
	v_mov_b32_e32 v39, 0
	v_mov_b32_e32 v40, 0
	v_mov_b32_e32 v41, 0
	s_cbranch_scc1 .LBB0_333
	global_load_dwordx4 v[38:41], v[174:175], off

; __device__ __forceinline__ u32x4 pack8(const f32x4 a, const f32x4 b) { u32x4 w; w.x = cvt_pk_bf16(a.x, a.y); w.y = cvt_pk_bf16(a.z, a.w); w.z = cvt_pk_bf16(b.x, b.y); w.w = cvt_pk_bf16(b.z, b.w); return w; }
; __device__ __forceinline__ f32x4 silu4(const f32x4 p) { f32x4 r; r.x = siluf(p.x); r.y = siluf(p.y); r.z = siluf(p.z); r.w = siluf(p.w); return r; }
; __device__ __forceinline__ float siluf(float x) { return x * __builtin_amdgcn_rcpf(1.f + __expf(-x)); }
;     __device__ __forceinline__ void operator()(f32x4 (&acc)[2][2][4][2], const pg8::Unit& u, int ui, int wr, int wc, int fr, int fq) const {
;     ...
;                     f32x4 p0 = acc[ai][bj][m][0] * r + sw[bj][0], p1 = acc[ai][bj][m][1] * r + sw[bj][1];
;                     const size_t o = (size_t)row * DH + colt + bj * 128;
;                     if (grp == 0) { *(u32x4*)(Q + o) = pack8(silu4(p0) * QSCALE, silu4(p1) * QSCALE); }
.LBB0_355:
	s_and_b64 vcc, exec, s[8:9]
	s_cbranch_vccz .LBB0_357
	v_pk_mul_f32 v[156:157], v[154:155], s[100:101] op_sel_hi:[1,0]
	v_exp_f32_e32 v156, v156
	v_exp_f32_e32 v157, v157
	v_pk_mul_f32 v[158:159], v[152:153], s[100:101] op_sel_hi:[1,0]
	v_exp_f32_e32 v158, v158
	v_exp_f32_e32 v159, v159
	v_pk_add_f32 v[156:157], v[156:157], 1.0 op_sel_hi:[1,0]
	v_rcp_f32_e32 v156, v156
	v_rcp_f32_e32 v157, v157
	v_pk_add_f32 v[158:159], v[158:159], 1.0 op_sel_hi:[1,0]
	v_rcp_f32_e32 v158, v158
	v_rcp_f32_e32 v159, v159
	v_pk_mul_f32 v[154:155], v[154:155], v[156:157]
	v_pk_mul_f32 v[156:157], v[150:151], s[100:101] op_sel_hi:[1,0]
	v_exp_f32_e32 v156, v156
	v_exp_f32_e32 v157, v157
	v_pk_mul_f32 v[152:153], v[152:153], v[158:159]
	v_pk_mul_f32 v[158:159], v[148:149], s[100:101] op_sel_hi:[1,0]
	v_exp_f32_e32 v158, v158
	v_exp_f32_e32 v159, v159
	v_pk_add_f32 v[156:157], v[156:157], 1.0 op_sel_hi:[1,0]
	v_rcp_f32_e32 v156, v156
	v_rcp_f32_e32 v157, v157
	v_pk_add_f32 v[158:159], v[158:159], 1.0 op_sel_hi:[1,0]
	v_rcp_f32_e32 v158, v158
	v_rcp_f32_e32 v159, v159
	v_pk_mul_f32 v[150:151], v[150:151], v[156:157]
	v_lshl_add_u64 v[146:147], v[146:147], 1, s[20:21]
	v_pk_mul_f32 v[150:151], v[150:151], s[50:51] op_sel_hi:[1,0]
	v_pk_mul_f32 v[148:149], v[148:149], v[158:159]
	v_pk_mul_f32 v[152:153], v[152:153], s[50:51] op_sel_hi:[1,0]
	v_pk_mul_f32 v[154:155], v[154:155], s[50:51] op_sel_hi:[1,0]
	v_pk_mul_f32 v[156:157], v[148:149], s[50:51] op_sel_hi:[1,0]
	v_cvt_pk_bf16_f32 v148, v154, v155
	v_cvt_pk_bf16_f32 v149, v152, v153
	v_cvt_pk_bf16_f32 v150, v150, v151
	s_nop 0
	v_cvt_pk_bf16_f32 v151, v156, v157
	global_store_dwordx4 v[146:147], v[148:151], off

; __device__ __forceinline__ u32x4 pack8(const f32x4 a, const f32x4 b) { u32x4 w; w.x = cvt_pk_bf16(a.x, a.y); w.y = cvt_pk_bf16(a.z, a.w); w.z = cvt_pk_bf16(b.x, b.y); w.w = cvt_pk_bf16(b.z, b.w); return w; }
; __device__ __forceinline__ f32x4 silu4(const f32x4 p) { f32x4 r; r.x = siluf(p.x); r.y = siluf(p.y); r.z = siluf(p.z); r.w = siluf(p.w); return r; }
; __device__ __forceinline__ float siluf(float x) { return x * __builtin_amdgcn_rcpf(1.f + __expf(-x)); }
;     __device__ __forceinline__ void operator()(f32x4 (&acc)[2][2][4][2], const pg8::Unit& u, int ui, int wr, int wc, int fr, int fq) const {
;     ...
;                     f32x4 p0 = acc[ai][bj][m][0] * r + sw[bj][0], p1 = acc[ai][bj][m][1] * r + sw[bj][1];
;                     const size_t o = (size_t)row * DH + colt + bj * 128;
;                     if (grp == 0) { *(u32x4*)(Q + o) = pack8(silu4(p0) * QSCALE, silu4(p1) * QSCALE); }
.LBB0_373:
	s_and_b64 vcc, exec, s[8:9]
	s_cbranch_vccz .LBB0_375
	v_pk_mul_f32 v[140:141], v[138:139], s[100:101] op_sel_hi:[1,0]
	v_exp_f32_e32 v140, v140
	v_exp_f32_e32 v141, v141
	v_pk_mul_f32 v[142:143], v[136:137], s[100:101] op_sel_hi:[1,0]
	v_exp_f32_e32 v142, v142
	v_exp_f32_e32 v143, v143
	v_pk_add_f32 v[140:141], v[140:141], 1.0 op_sel_hi:[1,0]
	v_rcp_f32_e32 v140, v140
	v_rcp_f32_e32 v141, v141
	v_pk_add_f32 v[142:143], v[142:143], 1.0 op_sel_hi:[1,0]
	v_rcp_f32_e32 v142, v142
	v_rcp_f32_e32 v143, v143
	v_pk_mul_f32 v[138:139], v[138:139], v[140:141]
	v_pk_mul_f32 v[140:141], v[134:135], s[100:101] op_sel_hi:[1,0]
	v_exp_f32_e32 v140, v140
	v_exp_f32_e32 v141, v141
	v_pk_mul_f32 v[136:137], v[136:137], v[142:143]
	v_pk_mul_f32 v[142:143], v[132:133], s[100:101] op_sel_hi:[1,0]
	v_exp_f32_e32 v142, v142
	v_exp_f32_e32 v143, v143
	v_pk_add_f32 v[140:141], v[140:141], 1.0 op_sel_hi:[1,0]
	v_rcp_f32_e32 v140, v140
	v_rcp_f32_e32 v141, v141
	v_pk_add_f32 v[142:143], v[142:143], 1.0 op_sel_hi:[1,0]
	v_rcp_f32_e32 v142, v142
	v_rcp_f32_e32 v143, v143
	v_pk_mul_f32 v[134:135], v[134:135], v[140:141]
	v_lshl_add_u64 v[130:131], v[130:131], 1, s[20:21]
	v_pk_mul_f32 v[134:135], v[134:135], s[50:51] op_sel_hi:[1,0]
	v_pk_mul_f32 v[132:133], v[132:133], v[142:143]
	v_pk_mul_f32 v[136:137], v[136:137], s[50:51] op_sel_hi:[1,0]
	v_pk_mul_f32 v[138:139], v[138:139], s[50:51] op_sel_hi:[1,0]
	v_pk_mul_f32 v[140:141], v[132:133], s[50:51] op_sel_hi:[1,0]
	v_cvt_pk_bf16_f32 v132, v138, v139
	v_cvt_pk_bf16_f32 v133, v136, v137
	v_cvt_pk_bf16_f32 v134, v134, v135
	s_nop 0
	v_cvt_pk_bf16_f32 v135, v140, v141
	global_store_dwordx4 v[130:131], v[132:135], off

; __device__ __forceinline__ u32x4 pack8(const f32x4 a, const f32x4 b) { u32x4 w; w.x = cvt_pk_bf16(a.x, a.y); w.y = cvt_pk_bf16(a.z, a.w); w.z = cvt_pk_bf16(b.x, b.y); w.w = cvt_pk_bf16(b.z, b.w); return w; }
; __device__ __forceinline__ f32x4 silu4(const f32x4 p) { f32x4 r; r.x = siluf(p.x); r.y = siluf(p.y); r.z = siluf(p.z); r.w = siluf(p.w); return r; }
; __device__ __forceinline__ float siluf(float x) { return x * __builtin_amdgcn_rcpf(1.f + __expf(-x)); }
;     __device__ __forceinline__ void operator()(f32x4 (&acc)[2][2][4][2], const pg8::Unit& u, int ui, int wr, int wc, int fr, int fq) const {
;     ...
;                     f32x4 p0 = acc[ai][bj][m][0] * r + sw[bj][0], p1 = acc[ai][bj][m][1] * r + sw[bj][1];
;                     const size_t o = (size_t)row * DH + colt + bj * 128;
;                     if (grp == 0) { *(u32x4*)(Q + o) = pack8(silu4(p0) * QSCALE, silu4(p1) * QSCALE); }
.LBB0_391:
	s_and_b64 vcc, exec, s[8:9]
	s_cbranch_vccz .LBB0_393
	v_pk_mul_f32 v[124:125], v[122:123], s[100:101] op_sel_hi:[1,0]
	v_exp_f32_e32 v124, v124
	v_exp_f32_e32 v125, v125
	v_pk_mul_f32 v[126:127], v[120:121], s[100:101] op_sel_hi:[1,0]
	v_exp_f32_e32 v126, v126
	v_exp_f32_e32 v127, v127
	v_pk_add_f32 v[124:125], v[124:125], 1.0 op_sel_hi:[1,0]
	v_rcp_f32_e32 v124, v124
	v_rcp_f32_e32 v125, v125
	v_pk_add_f32 v[126:127], v[126:127], 1.0 op_sel_hi:[1,0]
	v_rcp_f32_e32 v126, v126
	v_rcp_f32_e32 v127, v127
	v_pk_mul_f32 v[122:123], v[122:123], v[124:125]
	v_pk_mul_f32 v[124:125], v[118:119], s[100:101] op_sel_hi:[1,0]
	v_exp_f32_e32 v124, v124
	v_exp_f32_e32 v125, v125
	v_pk_mul_f32 v[120:121], v[120:121], v[126:127]
	v_pk_mul_f32 v[126:127], v[116:117], s[100:101] op_sel_hi:[1,0]
	v_exp_f32_e32 v126, v126
	v_exp_f32_e32 v127, v127
	v_pk_add_f32 v[124:125], v[124:125], 1.0 op_sel_hi:[1,0]
	v_rcp_f32_e32 v124, v124
	v_rcp_f32_e32 v125, v125
	v_pk_add_f32 v[126:127], v[126:127], 1.0 op_sel_hi:[1,0]
	v_rcp_f32_e32 v126, v126
	v_rcp_f32_e32 v127, v127
	v_pk_mul_f32 v[118:119], v[118:119], v[124:125]
	v_lshl_add_u64 v[114:115], v[114:115], 1, s[20:21]
	v_pk_mul_f32 v[118:119], v[118:119], s[50:51] op_sel_hi:[1,0]
	v_pk_mul_f32 v[116:117], v[116:117], v[126:127]
	v_pk_mul_f32 v[120:121], v[120:121], s[50:51] op_sel_hi:[1,0]
	v_pk_mul_f32 v[122:123], v[122:123], s[50:51] op_sel_hi:[1,0]
	v_pk_mul_f32 v[124:125], v[116:117], s[50:51] op_sel_hi:[1,0]
	v_cvt_pk_bf16_f32 v116, v122, v123
	v_cvt_pk_bf16_f32 v117, v120, v121
	v_cvt_pk_bf16_f32 v118, v118, v119
	s_nop 0
	v_cvt_pk_bf16_f32 v119, v124, v125
	global_store_dwordx4 v[114:115], v[116:119], off

; __device__ __forceinline__ u32x4 pack8(const f32x4 a, const f32x4 b) { u32x4 w; w.x = cvt_pk_bf16(a.x, a.y); w.y = cvt_pk_bf16(a.z, a.w); w.z = cvt_pk_bf16(b.x, b.y); w.w = cvt_pk_bf16(b.z, b.w); return w; }
; __device__ __forceinline__ f32x4 silu4(const f32x4 p) { f32x4 r; r.x = siluf(p.x); r.y = siluf(p.y); r.z = siluf(p.z); r.w = siluf(p.w); return r; }
; __device__ __forceinline__ float siluf(float x) { return x * __builtin_amdgcn_rcpf(1.f + __expf(-x)); }
;     __device__ __forceinline__ void operator()(f32x4 (&acc)[2][2][4][2], const pg8::Unit& u, int ui, int wr, int wc, int fr, int fq) const {
;     ...
;                     f32x4 p0 = acc[ai][bj][m][0] * r + sw[bj][0], p1 = acc[ai][bj][m][1] * r + sw[bj][1];
;                     const size_t o = (size_t)row * DH + colt + bj * 128;
;                     if (grp == 0) { *(u32x4*)(Q + o) = pack8(silu4(p0) * QSCALE, silu4(p1) * QSCALE); }
.LBB0_409:
	s_and_b64 vcc, exec, s[8:9]
	s_cbranch_vccz .LBB0_411
	v_pk_mul_f32 v[108:109], v[106:107], s[100:101] op_sel_hi:[1,0]
	v_exp_f32_e32 v108, v108
	v_exp_f32_e32 v109, v109
	v_pk_mul_f32 v[110:111], v[104:105], s[100:101] op_sel_hi:[1,0]
	v_exp_f32_e32 v110, v110
	v_exp_f32_e32 v111, v111
	v_pk_add_f32 v[108:109], v[108:109], 1.0 op_sel_hi:[1,0]
	v_rcp_f32_e32 v108, v108
	v_rcp_f32_e32 v109, v109
	v_pk_add_f32 v[110:111], v[110:111], 1.0 op_sel_hi:[1,0]
	v_rcp_f32_e32 v110, v110
	v_rcp_f32_e32 v111, v111
	v_pk_mul_f32 v[106:107], v[106:107], v[108:109]
	v_pk_mul_f32 v[108:109], v[102:103], s[100:101] op_sel_hi:[1,0]
	v_exp_f32_e32 v108, v108
	v_exp_f32_e32 v109, v109
	v_pk_mul_f32 v[104:105], v[104:105], v[110:111]
	v_pk_mul_f32 v[110:111], v[100:101], s[100:101] op_sel_hi:[1,0]
	v_exp_f32_e32 v110, v110
	v_exp_f32_e32 v111, v111
	v_pk_add_f32 v[108:109], v[108:109], 1.0 op_sel_hi:[1,0]
	v_rcp_f32_e32 v108, v108
	v_rcp_f32_e32 v109, v109
	v_pk_add_f32 v[110:111], v[110:111], 1.0 op_sel_hi:[1,0]
	v_rcp_f32_e32 v110, v110
	v_rcp_f32_e32 v111, v111
	v_pk_mul_f32 v[102:103], v[102:103], v[108:109]
	v_lshl_add_u64 v[98:99], v[98:99], 1, s[20:21]
	v_pk_mul_f32 v[102:103], v[102:103], s[50:51] op_sel_hi:[1,0]
	v_pk_mul_f32 v[100:101], v[100:101], v[110:111]
	v_pk_mul_f32 v[104:105], v[104:105], s[50:51] op_sel_hi:[1,0]
	v_pk_mul_f32 v[106:107], v[106:107], s[50:51] op_sel_hi:[1,0]
	v_pk_mul_f32 v[108:109], v[100:101], s[50:51] op_sel_hi:[1,0]
	v_cvt_pk_bf16_f32 v100, v106, v107
	v_cvt_pk_bf16_f32 v101, v104, v105
	v_cvt_pk_bf16_f32 v102, v102, v103
	s_nop 0
	v_cvt_pk_bf16_f32 v103, v108, v109
	global_store_dwordx4 v[98:99], v[100:103], off

; __device__ __forceinline__ u32x4 pack8(const f32x4 a, const f32x4 b) { u32x4 w; w.x = cvt_pk_bf16(a.x, a.y); w.y = cvt_pk_bf16(a.z, a.w); w.z = cvt_pk_bf16(b.x, b.y); w.w = cvt_pk_bf16(b.z, b.w); return w; }
; __device__ __forceinline__ f32x4 silu4(const f32x4 p) { f32x4 r; r.x = siluf(p.x); r.y = siluf(p.y); r.z = siluf(p.z); r.w = siluf(p.w); return r; }
; __device__ __forceinline__ float siluf(float x) { return x * __builtin_amdgcn_rcpf(1.f + __expf(-x)); }
;     __device__ __forceinline__ void operator()(f32x4 (&acc)[2][2][4][2], const pg8::Unit& u, int ui, int wr, int wc, int fr, int fq) const {
;     ...
;                     f32x4 p0 = acc[ai][bj][m][0] * r + sw[bj][0], p1 = acc[ai][bj][m][1] * r + sw[bj][1];
;                     const size_t o = (size_t)row * DH + colt + bj * 128;
;                     if (grp == 0) { *(u32x4*)(Q + o) = pack8(silu4(p0) * QSCALE, silu4(p1) * QSCALE); }
.LBB0_427:
	s_and_b64 vcc, exec, s[8:9]
	s_cbranch_vccz .LBB0_429
	v_pk_mul_f32 v[92:93], v[90:91], s[100:101] op_sel_hi:[1,0]
	v_exp_f32_e32 v92, v92
	v_exp_f32_e32 v93, v93
	v_pk_mul_f32 v[94:95], v[88:89], s[100:101] op_sel_hi:[1,0]
	v_exp_f32_e32 v94, v94
	v_exp_f32_e32 v95, v95
	v_pk_add_f32 v[92:93], v[92:93], 1.0 op_sel_hi:[1,0]
	v_rcp_f32_e32 v92, v92
	v_rcp_f32_e32 v93, v93
	v_pk_add_f32 v[94:95], v[94:95], 1.0 op_sel_hi:[1,0]
	v_rcp_f32_e32 v94, v94
	v_rcp_f32_e32 v95, v95
	v_pk_mul_f32 v[90:91], v[90:91], v[92:93]
	v_pk_mul_f32 v[92:93], v[86:87], s[100:101] op_sel_hi:[1,0]
	v_exp_f32_e32 v92, v92
	v_exp_f32_e32 v93, v93
	v_pk_mul_f32 v[88:89], v[88:89], v[94:95]
	v_pk_mul_f32 v[94:95], v[84:85], s[100:101] op_sel_hi:[1,0]
	v_exp_f32_e32 v94, v94
	v_exp_f32_e32 v95, v95
	v_pk_add_f32 v[92:93], v[92:93], 1.0 op_sel_hi:[1,0]
	v_rcp_f32_e32 v92, v92
	v_rcp_f32_e32 v93, v93
	v_pk_add_f32 v[94:95], v[94:95], 1.0 op_sel_hi:[1,0]
	v_rcp_f32_e32 v94, v94
	v_rcp_f32_e32 v95, v95
	v_pk_mul_f32 v[86:87], v[86:87], v[92:93]
	v_lshl_add_u64 v[82:83], v[82:83], 1, s[20:21]
	v_pk_mul_f32 v[86:87], v[86:87], s[50:51] op_sel_hi:[1,0]
	v_pk_mul_f32 v[84:85], v[84:85], v[94:95]
	v_pk_mul_f32 v[88:89], v[88:89], s[50:51] op_sel_hi:[1,0]
	v_pk_mul_f32 v[90:91], v[90:91], s[50:51] op_sel_hi:[1,0]
	v_pk_mul_f32 v[92:93], v[84:85], s[50:51] op_sel_hi:[1,0]
	v_cvt_pk_bf16_f32 v84, v90, v91
	v_cvt_pk_bf16_f32 v85, v88, v89
	v_cvt_pk_bf16_f32 v86, v86, v87
	s_nop 0
	v_cvt_pk_bf16_f32 v87, v92, v93
	global_store_dwordx4 v[82:83], v[84:87], off

; __device__ __forceinline__ u32x4 pack8(const f32x4 a, const f32x4 b) { u32x4 w; w.x = cvt_pk_bf16(a.x, a.y); w.y = cvt_pk_bf16(a.z, a.w); w.z = cvt_pk_bf16(b.x, b.y); w.w = cvt_pk_bf16(b.z, b.w); return w; }
; __device__ __forceinline__ f32x4 silu4(const f32x4 p) { f32x4 r; r.x = siluf(p.x); r.y = siluf(p.y); r.z = siluf(p.z); r.w = siluf(p.w); return r; }
; __device__ __forceinline__ float siluf(float x) { return x * __builtin_amdgcn_rcpf(1.f + __expf(-x)); }
;     __device__ __forceinline__ void operator()(f32x4 (&acc)[2][2][4][2], const pg8::Unit& u, int ui, int wr, int wc, int fr, int fq) const {
;     ...
;                     f32x4 p0 = acc[ai][bj][m][0] * r + sw[bj][0], p1 = acc[ai][bj][m][1] * r + sw[bj][1];
;                     const size_t o = (size_t)row * DH + colt + bj * 128;
;                     if (grp == 0) { *(u32x4*)(Q + o) = pack8(silu4(p0) * QSCALE, silu4(p1) * QSCALE); }
.LBB0_445:
	s_and_b64 vcc, exec, s[8:9]
	s_cbranch_vccz .LBB0_447
	v_pk_mul_f32 v[76:77], v[74:75], s[100:101] op_sel_hi:[1,0]
	v_exp_f32_e32 v76, v76
	v_exp_f32_e32 v77, v77
	v_pk_mul_f32 v[78:79], v[72:73], s[100:101] op_sel_hi:[1,0]
	v_exp_f32_e32 v78, v78
	v_exp_f32_e32 v79, v79
	v_pk_add_f32 v[76:77], v[76:77], 1.0 op_sel_hi:[1,0]
	v_rcp_f32_e32 v76, v76
	v_rcp_f32_e32 v77, v77
	v_pk_add_f32 v[78:79], v[78:79], 1.0 op_sel_hi:[1,0]
	v_rcp_f32_e32 v78, v78
	v_rcp_f32_e32 v79, v79
	v_pk_mul_f32 v[74:75], v[74:75], v[76:77]
	v_pk_mul_f32 v[76:77], v[70:71], s[100:101] op_sel_hi:[1,0]
	v_exp_f32_e32 v76, v76
	v_exp_f32_e32 v77, v77
	v_pk_mul_f32 v[72:73], v[72:73], v[78:79]
	v_pk_mul_f32 v[78:79], v[68:69], s[100:101] op_sel_hi:[1,0]
	v_exp_f32_e32 v78, v78
	v_exp_f32_e32 v79, v79
	v_pk_add_f32 v[76:77], v[76:77], 1.0 op_sel_hi:[1,0]
	v_rcp_f32_e32 v76, v76
	v_rcp_f32_e32 v77, v77
	v_pk_add_f32 v[78:79], v[78:79], 1.0 op_sel_hi:[1,0]
	v_rcp_f32_e32 v78, v78
	v_rcp_f32_e32 v79, v79
	v_pk_mul_f32 v[70:71], v[70:71], v[76:77]
	v_lshl_add_u64 v[66:67], v[66:67], 1, s[20:21]
	v_pk_mul_f32 v[70:71], v[70:71], s[50:51] op_sel_hi:[1,0]
	v_pk_mul_f32 v[68:69], v[68:69], v[78:79]
	v_pk_mul_f32 v[72:73], v[72:73], s[50:51] op_sel_hi:[1,0]
	v_pk_mul_f32 v[74:75], v[74:75], s[50:51] op_sel_hi:[1,0]
	v_pk_mul_f32 v[76:77], v[68:69], s[50:51] op_sel_hi:[1,0]
	v_cvt_pk_bf16_f32 v68, v74, v75
	v_cvt_pk_bf16_f32 v69, v72, v73
	v_cvt_pk_bf16_f32 v70, v70, v71
	s_nop 0
	v_cvt_pk_bf16_f32 v71, v76, v77
	global_store_dwordx4 v[66:67], v[68:71], off

; __device__ __forceinline__ u32x4 pack8(const f32x4 a, const f32x4 b) { u32x4 w; w.x = cvt_pk_bf16(a.x, a.y); w.y = cvt_pk_bf16(a.z, a.w); w.z = cvt_pk_bf16(b.x, b.y); w.w = cvt_pk_bf16(b.z, b.w); return w; }
; __device__ __forceinline__ f32x4 silu4(const f32x4 p) { f32x4 r; r.x = siluf(p.x); r.y = siluf(p.y); r.z = siluf(p.z); r.w = siluf(p.w); return r; }
; __device__ __forceinline__ float siluf(float x) { return x * __builtin_amdgcn_rcpf(1.f + __expf(-x)); }
;     __device__ __forceinline__ void operator()(f32x4 (&acc)[2][2][4][2], const pg8::Unit& u, int ui, int wr, int wc, int fr, int fq) const {
;     ...
;                     f32x4 p0 = acc[ai][bj][m][0] * r + sw[bj][0], p1 = acc[ai][bj][m][1] * r + sw[bj][1];
;                     const size_t o = (size_t)row * DH + colt + bj * 128;
;                     if (grp == 0) { *(u32x4*)(Q + o) = pack8(silu4(p0) * QSCALE, silu4(p1) * QSCALE); }
.LBB0_463:
	s_and_b64 vcc, exec, s[8:9]
	s_cbranch_vccz .LBB0_465
	v_pk_mul_f32 v[60:61], v[58:59], s[100:101] op_sel_hi:[1,0]
	v_exp_f32_e32 v60, v60
	v_exp_f32_e32 v61, v61
	v_pk_mul_f32 v[62:63], v[48:49], s[100:101] op_sel_hi:[1,0]
	v_exp_f32_e32 v62, v62
	v_exp_f32_e32 v63, v63
	v_pk_add_f32 v[60:61], v[60:61], 1.0 op_sel_hi:[1,0]
	v_rcp_f32_e32 v60, v60
	v_rcp_f32_e32 v61, v61
	v_pk_add_f32 v[62:63], v[62:63], 1.0 op_sel_hi:[1,0]
	v_rcp_f32_e32 v62, v62
	v_rcp_f32_e32 v63, v63
	v_pk_mul_f32 v[58:59], v[58:59], v[60:61]
	v_pk_mul_f32 v[60:61], v[46:47], s[100:101] op_sel_hi:[1,0]
	v_exp_f32_e32 v60, v60
	v_exp_f32_e32 v61, v61
	v_pk_mul_f32 v[48:49], v[48:49], v[62:63]
	v_pk_mul_f32 v[62:63], v[44:45], s[100:101] op_sel_hi:[1,0]
	v_exp_f32_e32 v62, v62
	v_exp_f32_e32 v63, v63
	v_pk_add_f32 v[60:61], v[60:61], 1.0 op_sel_hi:[1,0]
	v_rcp_f32_e32 v60, v60
	v_rcp_f32_e32 v61, v61
	v_pk_add_f32 v[62:63], v[62:63], 1.0 op_sel_hi:[1,0]
	v_rcp_f32_e32 v62, v62
	v_rcp_f32_e32 v63, v63
	v_pk_mul_f32 v[46:47], v[46:47], v[60:61]
	v_lshl_add_u64 v[42:43], v[42:43], 1, s[20:21]
	v_pk_mul_f32 v[46:47], v[46:47], s[50:51] op_sel_hi:[1,0]
	v_pk_mul_f32 v[44:45], v[44:45], v[62:63]
	v_pk_mul_f32 v[48:49], v[48:49], s[50:51] op_sel_hi:[1,0]
	v_pk_mul_f32 v[58:59], v[58:59], s[50:51] op_sel_hi:[1,0]
	v_pk_mul_f32 v[60:61], v[44:45], s[50:51] op_sel_hi:[1,0]
	v_cvt_pk_bf16_f32 v44, v58, v59
	v_cvt_pk_bf16_f32 v45, v48, v49
	v_cvt_pk_bf16_f32 v46, v46, v47
	s_nop 0
	v_cvt_pk_bf16_f32 v47, v60, v61
	global_store_dwordx4 v[42:43], v[44:47], off

; __device__ __forceinline__ u32x4 pack8(const f32x4 a, const f32x4 b) { u32x4 w; w.x = cvt_pk_bf16(a.x, a.y); w.y = cvt_pk_bf16(a.z, a.w); w.z = cvt_pk_bf16(b.x, b.y); w.w = cvt_pk_bf16(b.z, b.w); return w; }
; __device__ __forceinline__ f32x4 silu4(const f32x4 p) { f32x4 r; r.x = siluf(p.x); r.y = siluf(p.y); r.z = siluf(p.z); r.w = siluf(p.w); return r; }
; __device__ __forceinline__ float siluf(float x) { return x * __builtin_amdgcn_rcpf(1.f + __expf(-x)); }
;     __device__ __forceinline__ void operator()(f32x4 (&acc)[2][2][4][2], const pg8::Unit& u, int ui, int wr, int wc, int fr, int fq) const {
;     ...
;                     f32x4 p0 = acc[ai][bj][m][0] * r + sw[bj][0], p1 = acc[ai][bj][m][1] * r + sw[bj][1];
;                     const size_t o = (size_t)row * DH + colt + bj * 128;
;                     if (grp == 0) { *(u32x4*)(Q + o) = pack8(silu4(p0) * QSCALE, silu4(p1) * QSCALE); }
.LBB0_472:
	s_and_b64 vcc, exec, s[8:9]
	s_cbranch_vccz .LBB0_474
	v_pk_mul_f32 v[26:27], v[34:35], s[100:101] op_sel_hi:[1,0]
	v_exp_f32_e32 v26, v26
	v_exp_f32_e32 v27, v27
	v_pk_mul_f32 v[28:29], v[36:37], s[100:101] op_sel_hi:[1,0]
	v_exp_f32_e32 v28, v28
	v_exp_f32_e32 v29, v29
	v_pk_add_f32 v[26:27], v[26:27], 1.0 op_sel_hi:[1,0]
	v_rcp_f32_e32 v26, v26
	v_rcp_f32_e32 v27, v27
	v_pk_add_f32 v[28:29], v[28:29], 1.0 op_sel_hi:[1,0]
	v_rcp_f32_e32 v28, v28
	v_rcp_f32_e32 v29, v29
	v_pk_mul_f32 v[26:27], v[34:35], v[26:27]
	v_pk_mul_f32 v[34:35], v[30:31], s[100:101] op_sel_hi:[1,0]
	v_exp_f32_e32 v34, v34
	v_exp_f32_e32 v35, v35
	v_pk_mul_f32 v[28:29], v[36:37], v[28:29]
	v_pk_mul_f32 v[36:37], v[32:33], s[100:101] op_sel_hi:[1,0]
	v_exp_f32_e32 v36, v36
	v_exp_f32_e32 v37, v37
	v_pk_add_f32 v[34:35], v[34:35], 1.0 op_sel_hi:[1,0]
	v_rcp_f32_e32 v34, v34
	v_rcp_f32_e32 v35, v35
	v_pk_add_f32 v[36:37], v[36:37], 1.0 op_sel_hi:[1,0]
	v_rcp_f32_e32 v36, v36
	v_rcp_f32_e32 v37, v37
	v_pk_mul_f32 v[30:31], v[30:31], v[34:35]
	v_pk_mul_f32 v[28:29], v[28:29], s[50:51] op_sel_hi:[1,0]
	v_pk_mul_f32 v[26:27], v[26:27], s[50:51] op_sel_hi:[1,0]
	v_pk_mul_f32 v[30:31], v[30:31], s[50:51] op_sel_hi:[1,0]
	v_pk_mul_f32 v[32:33], v[32:33], v[36:37]
	v_cvt_pk_bf16_f32 v26, v26, v27
	v_cvt_pk_bf16_f32 v27, v28, v29
	v_cvt_pk_bf16_f32 v28, v30, v31
	v_lshl_add_u64 v[30:31], v[42:43], 1, s[20:21]
	v_pk_mul_f32 v[32:33], v[32:33], s[50:51] op_sel_hi:[1,0]
	s_nop 0
	v_cvt_pk_bf16_f32 v29, v32, v33
	global_store_dwordx4 v[30:31], v[26:29], off

; __device__ __forceinline__ u32x4 pack8(const f32x4 a, const f32x4 b) { u32x4 w; w.x = cvt_pk_bf16(a.x, a.y); w.y = cvt_pk_bf16(a.z, a.w); w.z = cvt_pk_bf16(b.x, b.y); w.w = cvt_pk_bf16(b.z, b.w); return w; }
; __device__ __forceinline__ f32x4 silu4(const f32x4 p) { f32x4 r; r.x = siluf(p.x); r.y = siluf(p.y); r.z = siluf(p.z); r.w = siluf(p.w); return r; }
; __device__ __forceinline__ float siluf(float x) { return x * __builtin_amdgcn_rcpf(1.f + __expf(-x)); }
;     __device__ __forceinline__ void operator()(f32x4 (&acc)[2][2][4][2], const pg8::Unit& u, int ui, int wr, int wc, int fr, int fq) const {
;     ...
;                     f32x4 p0 = acc[ai][bj][m][0] * r + sw[bj][0], p1 = acc[ai][bj][m][1] * r + sw[bj][1];
;                     const size_t o = (size_t)row * DH + colt + bj * 128;
;                     if (grp == 0) { *(u32x4*)(Q + o) = pack8(silu4(p0) * QSCALE, silu4(p1) * QSCALE); }
.LBB0_483:
	v_pk_mul_f32 v[12:13], v[8:9], s[100:101] op_sel_hi:[1,0]
	v_exp_f32_e32 v12, v12
	v_exp_f32_e32 v13, v13
	v_pk_mul_f32 v[14:15], v[6:7], s[100:101] op_sel_hi:[1,0]
	v_pk_add_f32 v[12:13], v[12:13], 1.0 op_sel_hi:[1,0]
	v_rcp_f32_e32 v12, v12
	v_rcp_f32_e32 v13, v13
	v_exp_f32_e32 v14, v14
	v_exp_f32_e32 v15, v15
	v_pk_mul_f32 v[10:11], v[18:19], s[100:101] op_sel_hi:[1,0]
	v_pk_mul_f32 v[8:9], v[8:9], v[12:13]
	v_add_f32_e32 v12, 1.0, v14
	v_add_f32_e32 v13, 1.0, v15
	v_pk_mul_f32 v[14:15], v[4:5], s[100:101] op_sel_hi:[1,0]
	v_exp_f32_e32 v10, v10
	v_exp_f32_e32 v11, v11
	v_exp_f32_e32 v14, v14
	v_exp_f32_e32 v15, v15
	v_pk_add_f32 v[10:11], v[10:11], 1.0 op_sel_hi:[1,0]
	v_rcp_f32_e32 v12, v12
	v_rcp_f32_e32 v13, v13
	v_pk_add_f32 v[14:15], v[14:15], 1.0 op_sel_hi:[1,0]
	v_rcp_f32_e32 v10, v10
	v_rcp_f32_e32 v11, v11
	v_rcp_f32_e32 v14, v14
	v_rcp_f32_e32 v15, v15
	v_pk_mul_f32 v[6:7], v[6:7], v[12:13]
	v_pk_mul_f32 v[10:11], v[18:19], v[10:11]
	v_pk_mul_f32 v[6:7], v[6:7], s[50:51] op_sel_hi:[1,0]
	v_pk_mul_f32 v[4:5], v[4:5], v[14:15]
	v_lshl_add_u64 v[2:3], v[2:3], 1, s[20:21]
	v_pk_mul_f32 v[8:9], v[8:9], s[50:51] op_sel_hi:[1,0]
	v_pk_mul_f32 v[10:11], v[10:11], s[50:51] op_sel_hi:[1,0]
	v_pk_mul_f32 v[12:13], v[4:5], s[50:51] op_sel_hi:[1,0]
	v_cvt_pk_bf16_f32 v4, v10, v11
	v_cvt_pk_bf16_f32 v5, v8, v9
	v_cvt_pk_bf16_f32 v6, v6, v7
	s_nop 0
	v_cvt_pk_bf16_f32 v7, v12, v13
	global_store_dwordx4 v[2:3], v[4:7], off
	s_andn2_b64 vcc, exec, s[36:37]
	s_mov_b64 s[6:7], -1
	s_cbranch_vccnz .LBB0_324

; __device__ __forceinline__ float logf_of(float p, float lb) { const float sig = __builtin_amdgcn_rcpf(1.f + __expf(-p)); const float f = lb + (1.f - lb) * sig; return fmaxf(__logf(f), -60.f); }
; __device__ __forceinline__ u32x4 pack8(const f32x4 a, const f32x4 b) { u32x4 w; w.x = cvt_pk_bf16(a.x, a.y); w.y = cvt_pk_bf16(a.z, a.w); w.z = cvt_pk_bf16(b.x, b.y); w.w = cvt_pk_bf16(b.z, b.w); return w; }
; __device__ __forceinline__ f32x4 silu4(const f32x4 p) { f32x4 r; r.x = siluf(p.x); r.y = siluf(p.y); r.z = siluf(p.z); r.w = siluf(p.w); return r; }
; __device__ __forceinline__ void store_wt(void* p, const u32x4 v) { asm volatile("global_store_dwordx4 %0, %1, off sc1\n\ts_nop 2" :: "v"(p), "v"(v) : "memory"); }
; __device__ __forceinline__ float siluf(float x) { return x * __builtin_amdgcn_rcpf(1.f + __expf(-x)); }
;     __device__ __forceinline__ void operator()(f32x4 (&acc)[2][2][4][2], const pg8::Unit& u, int ui, int wr, int wc, int fr, int fq) const {
;     ...
;                     if (grp == 0) { *(u32x4*)(Q + o) = pack8(silu4(p0) * QSCALE, silu4(p1) * QSCALE); }
;                     else if (grp == 1) { f32x4 l0, l1; l0.x = logf_of(p0.x, lb[bj][0].x); l0.y = logf_of(p0.y, lb[bj][0].y); l0.z = logf_of(p0.z, lb[bj][0].z); l0.w = logf_of(p0.w, lb[bj][0].w);
;                         l1.x = logf_of(p1.x, lb[bj][1].x); l1.y = logf_of(p1.y, lb[bj][1].y); l1.z = logf_of(p1.z, lb[bj][1].z); l1.w = logf_of(p1.w, lb[bj][1].w);
;                         const f32x8_t ff = {l0.x, l0.y, l0.z, l0.w, l1.x, l1.y, l1.z, l1.w}; *(f16x8_t*)(LF + o) = __builtin_convertvector(ff, f16x8_t); }
;                     else if (grp == 2) { *(u32x4*)(V + o) = pack8(p0, p1); }
;                     else if (grp == 3) { *(u32x4*)(SG + o) = pack8(silu4(p0), silu4(p1)); }
;                     else { store_wt(U + o, pack8(p0, p1)); }
.LBB0_495:
	s_cmp_gt_i32 s29, 2
	s_cbranch_scc0 .LBB0_499
	s_cmp_eq_u32 s29, 3
	s_mov_b64 s[86:87], -1
	s_cbranch_scc0 .LBB0_498
	v_pk_mul_f32 v[156:157], v[154:155], s[100:101] op_sel_hi:[1,0]
	v_mul_f32_e32 v158, 0xbfb8aa3b, v152
	v_pk_mul_f32 v[160:161], v[150:151], s[100:101] op_sel_hi:[1,0]
	v_exp_f32_e32 v156, v156
	v_exp_f32_e32 v157, v157
	v_exp_f32_e32 v158, v158
	v_mul_f32_e32 v159, 0xbfb8aa3b, v153
	v_exp_f32_e32 v160, v160
	v_exp_f32_e32 v161, v161
	v_exp_f32_e32 v159, v159
	v_pk_mul_f32 v[178:179], v[148:149], s[100:101] op_sel_hi:[1,0]
	v_exp_f32_e32 v178, v178
	v_exp_f32_e32 v179, v179
	v_pk_add_f32 v[156:157], v[156:157], 1.0 op_sel_hi:[1,0]
	v_add_f32_e32 v158, 1.0, v158
	v_pk_add_f32 v[160:161], v[160:161], 1.0 op_sel_hi:[1,0]
	v_rcp_f32_e32 v156, v156
	v_rcp_f32_e32 v157, v157
	v_rcp_f32_e32 v158, v158
	v_add_f32_e32 v159, 1.0, v159
	v_rcp_f32_e32 v160, v160
	v_rcp_f32_e32 v161, v161
	v_rcp_f32_e32 v159, v159
	v_pk_add_f32 v[178:179], v[178:179], 1.0 op_sel_hi:[1,0]
	v_rcp_f32_e32 v178, v178
	v_rcp_f32_e32 v179, v179
	v_mul_f32_e32 v156, v154, v156
	v_mul_f32_e32 v157, v155, v157
	v_mul_f32_e32 v158, v152, v158
	v_mul_f32_e32 v160, v150, v160
	v_mul_f32_e32 v161, v151, v161
	v_mul_f32_e32 v159, v153, v159
	v_cvt_pk_bf16_f32 v156, v156, v157
	v_cvt_pk_bf16_f32 v157, v158, v159
	v_cvt_pk_bf16_f32 v158, v160, v161
	v_lshl_add_u64 v[160:161], v[146:147], 1, s[22:23]
	s_mov_b64 s[86:87], 0
	v_mul_f32_e32 v178, v148, v178
	v_mul_f32_e32 v179, v149, v179
	v_cvt_pk_bf16_f32 v159, v178, v179
	global_store_dwordx4 v[160:161], v[156:159], off

; __device__ __forceinline__ float logf_of(float p, float lb) { const float sig = __builtin_amdgcn_rcpf(1.f + __expf(-p)); const float f = lb + (1.f - lb) * sig; return fmaxf(__logf(f), -60.f); }
; __device__ __forceinline__ u32x4 pack8(const f32x4 a, const f32x4 b) { u32x4 w; w.x = cvt_pk_bf16(a.x, a.y); w.y = cvt_pk_bf16(a.z, a.w); w.z = cvt_pk_bf16(b.x, b.y); w.w = cvt_pk_bf16(b.z, b.w); return w; }
; __device__ __forceinline__ f32x4 silu4(const f32x4 p) { f32x4 r; r.x = siluf(p.x); r.y = siluf(p.y); r.z = siluf(p.z); r.w = siluf(p.w); return r; }
; __device__ __forceinline__ void store_wt(void* p, const u32x4 v) { asm volatile("global_store_dwordx4 %0, %1, off sc1\n\ts_nop 2" :: "v"(p), "v"(v) : "memory"); }
; __device__ __forceinline__ float siluf(float x) { return x * __builtin_amdgcn_rcpf(1.f + __expf(-x)); }
;     __device__ __forceinline__ void operator()(f32x4 (&acc)[2][2][4][2], const pg8::Unit& u, int ui, int wr, int wc, int fr, int fq) const {
;     ...
;                     if (grp == 0) { *(u32x4*)(Q + o) = pack8(silu4(p0) * QSCALE, silu4(p1) * QSCALE); }
;                     else if (grp == 1) { f32x4 l0, l1; l0.x = logf_of(p0.x, lb[bj][0].x); l0.y = logf_of(p0.y, lb[bj][0].y); l0.z = logf_of(p0.z, lb[bj][0].z); l0.w = logf_of(p0.w, lb[bj][0].w);
;                         l1.x = logf_of(p1.x, lb[bj][1].x); l1.y = logf_of(p1.y, lb[bj][1].y); l1.z = logf_of(p1.z, lb[bj][1].z); l1.w = logf_of(p1.w, lb[bj][1].w);
;                         const f32x8_t ff = {l0.x, l0.y, l0.z, l0.w, l1.x, l1.y, l1.z, l1.w}; *(f16x8_t*)(LF + o) = __builtin_convertvector(ff, f16x8_t); }
;                     else if (grp == 2) { *(u32x4*)(V + o) = pack8(p0, p1); }
;                     else if (grp == 3) { *(u32x4*)(SG + o) = pack8(silu4(p0), silu4(p1)); }
;                     else { store_wt(U + o, pack8(p0, p1)); }
.LBB0_504:
	s_cmp_gt_i32 s29, 2
	s_cbranch_scc0 .LBB0_508
	s_cmp_eq_u32 s29, 3
	s_mov_b64 s[86:87], -1
	s_cbranch_scc0 .LBB0_507
	v_mul_f32_e32 v150, 0xbfb8aa3b, v143
	v_mul_f32_e32 v151, 0xbfb8aa3b, v144
	v_mul_f32_e32 v152, 0xbfb8aa3b, v145
	v_mul_f32_e32 v153, 0xbfb8aa3b, v138
	v_mul_f32_e32 v154, 0xbfb8aa3b, v139
	v_mul_f32_e32 v155, 0xbfb8aa3b, v140
	v_mul_f32_e32 v149, 0xbfb8aa3b, v142
	v_exp_f32_e32 v150, v150
	v_exp_f32_e32 v151, v151
	v_exp_f32_e32 v152, v152
	v_exp_f32_e32 v153, v153
	v_exp_f32_e32 v154, v154
	v_exp_f32_e32 v155, v155
	v_mul_f32_e32 v156, 0xbfb8aa3b, v141
	v_exp_f32_e32 v149, v149
	v_exp_f32_e32 v156, v156
	v_pk_add_f32 v[150:151], v[150:151], 1.0 op_sel_hi:[1,0]
	v_pk_add_f32 v[152:153], v[152:153], 1.0 op_sel_hi:[1,0]
	v_pk_add_f32 v[154:155], v[154:155], 1.0 op_sel_hi:[1,0]
	v_add_f32_e32 v149, 1.0, v149
	v_rcp_f32_e32 v150, v150
	v_rcp_f32_e32 v151, v151
	v_rcp_f32_e32 v152, v152
	v_rcp_f32_e32 v153, v153
	v_rcp_f32_e32 v154, v154
	v_rcp_f32_e32 v155, v155
	v_add_f32_e32 v156, 1.0, v156
	v_rcp_f32_e32 v149, v149
	v_rcp_f32_e32 v156, v156
	v_mul_f32_e32 v150, v143, v150
	v_mul_f32_e32 v151, v144, v151
	v_mul_f32_e32 v152, v145, v152
	v_mul_f32_e32 v153, v138, v153
	v_mul_f32_e32 v154, v139, v154
	v_mul_f32_e32 v155, v140, v155
	v_mul_f32_e32 v149, v142, v149
	v_mul_f32_e32 v156, v141, v156
	v_cvt_pk_bf16_f32 v150, v149, v150
	v_cvt_pk_bf16_f32 v151, v151, v152
	v_cvt_pk_bf16_f32 v152, v153, v154
	v_cvt_pk_bf16_f32 v153, v155, v156
	v_lshl_add_u64 v[154:155], v[146:147], 1, s[22:23]
	s_mov_b64 s[86:87], 0
	global_store_dwordx4 v[154:155], v[150:153], off

; __device__ __forceinline__ unsigned cvt_pk_bf16(float lo, float hi) { unsigned r; asm volatile("v_cvt_pk_bf16_f32 %0, %1, %2" : "=v"(r) : "v"(lo), "v"(hi)); return r; }
; __device__ __forceinline__ float siluf(float x) { return x * __builtin_amdgcn_rcpf(1.f + __expf(-x)); }
; __device__ __forceinline__ float logf_of(float p, float lb) { const float sig = __builtin_amdgcn_rcpf(1.f + __expf(-p)); const float f = lb + (1.f - lb) * sig; return fmaxf(__logf(f), -60.f); }
; __device__ __forceinline__ void store_wt(void* p, const u32x4 v) { asm volatile("global_store_dwordx4 %0, %1, off sc1\n\ts_nop 2" :: "v"(p), "v"(v) : "memory"); }
; __device__ __forceinline__ u32x4 pack8(const f32x4 a, const f32x4 b) { u32x4 w; w.x = cvt_pk_bf16(a.x, a.y); w.y = cvt_pk_bf16(a.z, a.w); w.z = cvt_pk_bf16(b.x, b.y); w.w = cvt_pk_bf16(b.z, b.w); return w; }
; __device__ __forceinline__ f32x4 silu4(const f32x4 p) { f32x4 r; r.x = siluf(p.x); r.y = siluf(p.y); r.z = siluf(p.z); r.w = siluf(p.w); return r; }
;     __device__ __forceinline__ void operator()(f32x4 (&acc)[2][2][4][2], const pg8::Unit& u, int ui, int wr, int wc, int fr, int fq) const {
;     ...
;                     if (grp == 0) { *(u32x4*)(Q + o) = pack8(silu4(p0) * QSCALE, silu4(p1) * QSCALE); }
;                     else if (grp == 1) { f32x4 l0, l1; l0.x = logf_of(p0.x, lb[bj][0].x); l0.y = logf_of(p0.y, lb[bj][0].y); l0.z = logf_of(p0.z, lb[bj][0].z); l0.w = logf_of(p0.w, lb[bj][0].w);
;                         l1.x = logf_of(p1.x, lb[bj][1].x); l1.y = logf_of(p1.y, lb[bj][1].y); l1.z = logf_of(p1.z, lb[bj][1].z); l1.w = logf_of(p1.w, lb[bj][1].w);
;                         const f32x8_t ff = {l0.x, l0.y, l0.z, l0.w, l1.x, l1.y, l1.z, l1.w}; *(f16x8_t*)(LF + o) = __builtin_convertvector(ff, f16x8_t); }
;                     else if (grp == 2) { *(u32x4*)(V + o) = pack8(p0, p1); }
;                     else if (grp == 3) { *(u32x4*)(SG + o) = pack8(silu4(p0), silu4(p1)); }
;                     else { store_wt(U + o, pack8(p0, p1)); }
.LBB0_513:
	s_cmp_gt_i32 s29, 2
	s_cbranch_scc0 .LBB0_517
	s_cmp_eq_u32 s29, 3
	s_mov_b64 s[86:87], -1
	s_cbranch_scc0 .LBB0_516
	v_pk_mul_f32 v[140:141], v[138:139], s[100:101] op_sel_hi:[1,0]
	v_mul_f32_e32 v142, 0xbfb8aa3b, v136
	v_pk_mul_f32 v[144:145], v[134:135], s[100:101] op_sel_hi:[1,0]
	v_exp_f32_e32 v140, v140
	v_exp_f32_e32 v141, v141
	v_exp_f32_e32 v142, v142
	v_mul_f32_e32 v143, 0xbfb8aa3b, v137
	v_exp_f32_e32 v144, v144
	v_exp_f32_e32 v145, v145
	v_exp_f32_e32 v143, v143
	v_pk_mul_f32 v[148:149], v[132:133], s[100:101] op_sel_hi:[1,0]
	v_exp_f32_e32 v148, v148
	v_exp_f32_e32 v149, v149
	v_pk_add_f32 v[140:141], v[140:141], 1.0 op_sel_hi:[1,0]
	v_add_f32_e32 v142, 1.0, v142
	v_pk_add_f32 v[144:145], v[144:145], 1.0 op_sel_hi:[1,0]
	v_rcp_f32_e32 v140, v140
	v_rcp_f32_e32 v141, v141
	v_rcp_f32_e32 v142, v142
	v_add_f32_e32 v143, 1.0, v143
	v_rcp_f32_e32 v144, v144
	v_rcp_f32_e32 v145, v145
	v_rcp_f32_e32 v143, v143
	v_pk_add_f32 v[148:149], v[148:149], 1.0 op_sel_hi:[1,0]
	v_rcp_f32_e32 v148, v148
	v_rcp_f32_e32 v149, v149
	v_mul_f32_e32 v140, v138, v140
	v_mul_f32_e32 v141, v139, v141
	v_mul_f32_e32 v142, v136, v142
	v_mul_f32_e32 v144, v134, v144
	v_mul_f32_e32 v145, v135, v145
	v_mul_f32_e32 v143, v137, v143
	v_cvt_pk_bf16_f32 v140, v140, v141
	v_cvt_pk_bf16_f32 v141, v142, v143
	v_cvt_pk_bf16_f32 v142, v144, v145
	v_lshl_add_u64 v[144:145], v[130:131], 1, s[22:23]
	s_mov_b64 s[86:87], 0
	v_mul_f32_e32 v148, v132, v148
	v_mul_f32_e32 v149, v133, v149
	v_cvt_pk_bf16_f32 v143, v148, v149
	global_store_dwordx4 v[144:145], v[140:143], off

; __device__ __forceinline__ unsigned cvt_pk_bf16(float lo, float hi) { unsigned r; asm volatile("v_cvt_pk_bf16_f32 %0, %1, %2" : "=v"(r) : "v"(lo), "v"(hi)); return r; }
; __device__ __forceinline__ float siluf(float x) { return x * __builtin_amdgcn_rcpf(1.f + __expf(-x)); }
; __device__ __forceinline__ float logf_of(float p, float lb) { const float sig = __builtin_amdgcn_rcpf(1.f + __expf(-p)); const float f = lb + (1.f - lb) * sig; return fmaxf(__logf(f), -60.f); }
; __device__ __forceinline__ void store_wt(void* p, const u32x4 v) { asm volatile("global_store_dwordx4 %0, %1, off sc1\n\ts_nop 2" :: "v"(p), "v"(v) : "memory"); }
; __device__ __forceinline__ u32x4 pack8(const f32x4 a, const f32x4 b) { u32x4 w; w.x = cvt_pk_bf16(a.x, a.y); w.y = cvt_pk_bf16(a.z, a.w); w.z = cvt_pk_bf16(b.x, b.y); w.w = cvt_pk_bf16(b.z, b.w); return w; }
; __device__ __forceinline__ f32x4 silu4(const f32x4 p) { f32x4 r; r.x = siluf(p.x); r.y = siluf(p.y); r.z = siluf(p.z); r.w = siluf(p.w); return r; }
;     __device__ __forceinline__ void operator()(f32x4 (&acc)[2][2][4][2], const pg8::Unit& u, int ui, int wr, int wc, int fr, int fq) const {
;     ...
;                     if (grp == 0) { *(u32x4*)(Q + o) = pack8(silu4(p0) * QSCALE, silu4(p1) * QSCALE); }
;                     else if (grp == 1) { f32x4 l0, l1; l0.x = logf_of(p0.x, lb[bj][0].x); l0.y = logf_of(p0.y, lb[bj][0].y); l0.z = logf_of(p0.z, lb[bj][0].z); l0.w = logf_of(p0.w, lb[bj][0].w);
;                         l1.x = logf_of(p1.x, lb[bj][1].x); l1.y = logf_of(p1.y, lb[bj][1].y); l1.z = logf_of(p1.z, lb[bj][1].z); l1.w = logf_of(p1.w, lb[bj][1].w);
;                         const f32x8_t ff = {l0.x, l0.y, l0.z, l0.w, l1.x, l1.y, l1.z, l1.w}; *(f16x8_t*)(LF + o) = __builtin_convertvector(ff, f16x8_t); }
;                     else if (grp == 2) { *(u32x4*)(V + o) = pack8(p0, p1); }
;                     else if (grp == 3) { *(u32x4*)(SG + o) = pack8(silu4(p0), silu4(p1)); }
;                     else { store_wt(U + o, pack8(p0, p1)); }
.LBB0_522:
	s_cmp_gt_i32 s29, 2
	s_cbranch_scc0 .LBB0_526
	s_cmp_eq_u32 s29, 3
	s_mov_b64 s[86:87], -1
	s_cbranch_scc0 .LBB0_525
	v_mul_f32_e32 v134, 0xbfb8aa3b, v127
	v_mul_f32_e32 v135, 0xbfb8aa3b, v128
	v_mul_f32_e32 v136, 0xbfb8aa3b, v129
	v_mul_f32_e32 v137, 0xbfb8aa3b, v122
	v_mul_f32_e32 v138, 0xbfb8aa3b, v123
	v_mul_f32_e32 v139, 0xbfb8aa3b, v124
	v_mul_f32_e32 v133, 0xbfb8aa3b, v126
	v_exp_f32_e32 v134, v134
	v_exp_f32_e32 v135, v135
	v_exp_f32_e32 v136, v136
	v_exp_f32_e32 v137, v137
	v_exp_f32_e32 v138, v138
	v_exp_f32_e32 v139, v139
	v_mul_f32_e32 v140, 0xbfb8aa3b, v125
	v_exp_f32_e32 v133, v133
	v_exp_f32_e32 v140, v140
	v_pk_add_f32 v[134:135], v[134:135], 1.0 op_sel_hi:[1,0]
	v_pk_add_f32 v[136:137], v[136:137], 1.0 op_sel_hi:[1,0]
	v_pk_add_f32 v[138:139], v[138:139], 1.0 op_sel_hi:[1,0]
	v_add_f32_e32 v133, 1.0, v133
	v_rcp_f32_e32 v134, v134
	v_rcp_f32_e32 v135, v135
	v_rcp_f32_e32 v136, v136
	v_rcp_f32_e32 v137, v137
	v_rcp_f32_e32 v138, v138
	v_rcp_f32_e32 v139, v139
	v_add_f32_e32 v140, 1.0, v140
	v_rcp_f32_e32 v133, v133
	v_rcp_f32_e32 v140, v140
	v_mul_f32_e32 v134, v127, v134
	v_mul_f32_e32 v135, v128, v135
	v_mul_f32_e32 v136, v129, v136
	v_mul_f32_e32 v137, v122, v137
	v_mul_f32_e32 v138, v123, v138
	v_mul_f32_e32 v139, v124, v139
	v_mul_f32_e32 v133, v126, v133
	v_mul_f32_e32 v140, v125, v140
	v_cvt_pk_bf16_f32 v134, v133, v134
	v_cvt_pk_bf16_f32 v135, v135, v136
	v_cvt_pk_bf16_f32 v136, v137, v138
	v_cvt_pk_bf16_f32 v137, v139, v140
	v_lshl_add_u64 v[138:139], v[130:131], 1, s[22:23]
	s_mov_b64 s[86:87], 0
	global_store_dwordx4 v[138:139], v[134:137], off

; __device__ __forceinline__ unsigned cvt_pk_bf16(float lo, float hi) { unsigned r; asm volatile("v_cvt_pk_bf16_f32 %0, %1, %2" : "=v"(r) : "v"(lo), "v"(hi)); return r; }
; __device__ __forceinline__ float siluf(float x) { return x * __builtin_amdgcn_rcpf(1.f + __expf(-x)); }
; __device__ __forceinline__ float logf_of(float p, float lb) { const float sig = __builtin_amdgcn_rcpf(1.f + __expf(-p)); const float f = lb + (1.f - lb) * sig; return fmaxf(__logf(f), -60.f); }
; __device__ __forceinline__ void store_wt(void* p, const u32x4 v) { asm volatile("global_store_dwordx4 %0, %1, off sc1\n\ts_nop 2" :: "v"(p), "v"(v) : "memory"); }
; __device__ __forceinline__ u32x4 pack8(const f32x4 a, const f32x4 b) { u32x4 w; w.x = cvt_pk_bf16(a.x, a.y); w.y = cvt_pk_bf16(a.z, a.w); w.z = cvt_pk_bf16(b.x, b.y); w.w = cvt_pk_bf16(b.z, b.w); return w; }
; __device__ __forceinline__ f32x4 silu4(const f32x4 p) { f32x4 r; r.x = siluf(p.x); r.y = siluf(p.y); r.z = siluf(p.z); r.w = siluf(p.w); return r; }
;     __device__ __forceinline__ void operator()(f32x4 (&acc)[2][2][4][2], const pg8::Unit& u, int ui, int wr, int wc, int fr, int fq) const {
;     ...
;                     if (grp == 0) { *(u32x4*)(Q + o) = pack8(silu4(p0) * QSCALE, silu4(p1) * QSCALE); }
;                     else if (grp == 1) { f32x4 l0, l1; l0.x = logf_of(p0.x, lb[bj][0].x); l0.y = logf_of(p0.y, lb[bj][0].y); l0.z = logf_of(p0.z, lb[bj][0].z); l0.w = logf_of(p0.w, lb[bj][0].w);
;                         l1.x = logf_of(p1.x, lb[bj][1].x); l1.y = logf_of(p1.y, lb[bj][1].y); l1.z = logf_of(p1.z, lb[bj][1].z); l1.w = logf_of(p1.w, lb[bj][1].w);
;                         const f32x8_t ff = {l0.x, l0.y, l0.z, l0.w, l1.x, l1.y, l1.z, l1.w}; *(f16x8_t*)(LF + o) = __builtin_convertvector(ff, f16x8_t); }
;                     else if (grp == 2) { *(u32x4*)(V + o) = pack8(p0, p1); }
;                     else if (grp == 3) { *(u32x4*)(SG + o) = pack8(silu4(p0), silu4(p1)); }
;                     else { store_wt(U + o, pack8(p0, p1)); }
.LBB0_531:
	s_cmp_gt_i32 s29, 2
	s_cbranch_scc0 .LBB0_535
	s_cmp_eq_u32 s29, 3
	s_mov_b64 s[86:87], -1
	s_cbranch_scc0 .LBB0_534
	v_pk_mul_f32 v[124:125], v[122:123], s[100:101] op_sel_hi:[1,0]
	v_mul_f32_e32 v126, 0xbfb8aa3b, v120
	v_pk_mul_f32 v[128:129], v[118:119], s[100:101] op_sel_hi:[1,0]
	v_exp_f32_e32 v124, v124
	v_exp_f32_e32 v125, v125
	v_exp_f32_e32 v126, v126
	v_mul_f32_e32 v127, 0xbfb8aa3b, v121
	v_exp_f32_e32 v128, v128
	v_exp_f32_e32 v129, v129
	v_exp_f32_e32 v127, v127
	v_pk_mul_f32 v[132:133], v[116:117], s[100:101] op_sel_hi:[1,0]
	v_exp_f32_e32 v132, v132
	v_exp_f32_e32 v133, v133
	v_pk_add_f32 v[124:125], v[124:125], 1.0 op_sel_hi:[1,0]
	v_add_f32_e32 v126, 1.0, v126
	v_pk_add_f32 v[128:129], v[128:129], 1.0 op_sel_hi:[1,0]
	v_rcp_f32_e32 v124, v124
	v_rcp_f32_e32 v125, v125
	v_rcp_f32_e32 v126, v126
	v_add_f32_e32 v127, 1.0, v127
	v_rcp_f32_e32 v128, v128
	v_rcp_f32_e32 v129, v129
	v_rcp_f32_e32 v127, v127
	v_pk_add_f32 v[132:133], v[132:133], 1.0 op_sel_hi:[1,0]
	v_rcp_f32_e32 v132, v132
	v_rcp_f32_e32 v133, v133
	v_mul_f32_e32 v124, v122, v124
	v_mul_f32_e32 v125, v123, v125
	v_mul_f32_e32 v126, v120, v126
	v_mul_f32_e32 v128, v118, v128
	v_mul_f32_e32 v129, v119, v129
	v_mul_f32_e32 v127, v121, v127
	v_cvt_pk_bf16_f32 v124, v124, v125
	v_cvt_pk_bf16_f32 v125, v126, v127
	v_cvt_pk_bf16_f32 v126, v128, v129
	v_lshl_add_u64 v[128:129], v[114:115], 1, s[22:23]
	s_mov_b64 s[86:87], 0
	v_mul_f32_e32 v132, v116, v132
	v_mul_f32_e32 v133, v117, v133
	v_cvt_pk_bf16_f32 v127, v132, v133
	global_store_dwordx4 v[128:129], v[124:127], off

; __device__ __forceinline__ unsigned cvt_pk_bf16(float lo, float hi) { unsigned r; asm volatile("v_cvt_pk_bf16_f32 %0, %1, %2" : "=v"(r) : "v"(lo), "v"(hi)); return r; }
; __device__ __forceinline__ float siluf(float x) { return x * __builtin_amdgcn_rcpf(1.f + __expf(-x)); }
; __device__ __forceinline__ float logf_of(float p, float lb) { const float sig = __builtin_amdgcn_rcpf(1.f + __expf(-p)); const float f = lb + (1.f - lb) * sig; return fmaxf(__logf(f), -60.f); }
; __device__ __forceinline__ void store_wt(void* p, const u32x4 v) { asm volatile("global_store_dwordx4 %0, %1, off sc1\n\ts_nop 2" :: "v"(p), "v"(v) : "memory"); }
; __device__ __forceinline__ u32x4 pack8(const f32x4 a, const f32x4 b) { u32x4 w; w.x = cvt_pk_bf16(a.x, a.y); w.y = cvt_pk_bf16(a.z, a.w); w.z = cvt_pk_bf16(b.x, b.y); w.w = cvt_pk_bf16(b.z, b.w); return w; }
; __device__ __forceinline__ f32x4 silu4(const f32x4 p) { f32x4 r; r.x = siluf(p.x); r.y = siluf(p.y); r.z = siluf(p.z); r.w = siluf(p.w); return r; }
;     __device__ __forceinline__ void operator()(f32x4 (&acc)[2][2][4][2], const pg8::Unit& u, int ui, int wr, int wc, int fr, int fq) const {
;     ...
;                     if (grp == 0) { *(u32x4*)(Q + o) = pack8(silu4(p0) * QSCALE, silu4(p1) * QSCALE); }
;                     else if (grp == 1) { f32x4 l0, l1; l0.x = logf_of(p0.x, lb[bj][0].x); l0.y = logf_of(p0.y, lb[bj][0].y); l0.z = logf_of(p0.z, lb[bj][0].z); l0.w = logf_of(p0.w, lb[bj][0].w);
;                         l1.x = logf_of(p1.x, lb[bj][1].x); l1.y = logf_of(p1.y, lb[bj][1].y); l1.z = logf_of(p1.z, lb[bj][1].z); l1.w = logf_of(p1.w, lb[bj][1].w);
;                         const f32x8_t ff = {l0.x, l0.y, l0.z, l0.w, l1.x, l1.y, l1.z, l1.w}; *(f16x8_t*)(LF + o) = __builtin_convertvector(ff, f16x8_t); }
;                     else if (grp == 2) { *(u32x4*)(V + o) = pack8(p0, p1); }
;                     else if (grp == 3) { *(u32x4*)(SG + o) = pack8(silu4(p0), silu4(p1)); }
;                     else { store_wt(U + o, pack8(p0, p1)); }
.LBB0_540:
	s_cmp_gt_i32 s29, 2
	s_cbranch_scc0 .LBB0_544
	s_cmp_eq_u32 s29, 3
	s_mov_b64 s[86:87], -1
	s_cbranch_scc0 .LBB0_543
	v_mul_f32_e32 v118, 0xbfb8aa3b, v111
	v_mul_f32_e32 v119, 0xbfb8aa3b, v112
	v_mul_f32_e32 v120, 0xbfb8aa3b, v113
	v_mul_f32_e32 v121, 0xbfb8aa3b, v106
	v_mul_f32_e32 v122, 0xbfb8aa3b, v107
	v_mul_f32_e32 v123, 0xbfb8aa3b, v108
	v_mul_f32_e32 v117, 0xbfb8aa3b, v110
	v_exp_f32_e32 v118, v118
	v_exp_f32_e32 v119, v119
	v_exp_f32_e32 v120, v120
	v_exp_f32_e32 v121, v121
	v_exp_f32_e32 v122, v122
	v_exp_f32_e32 v123, v123
	v_mul_f32_e32 v124, 0xbfb8aa3b, v109
	v_exp_f32_e32 v117, v117
	v_exp_f32_e32 v124, v124
	v_pk_add_f32 v[118:119], v[118:119], 1.0 op_sel_hi:[1,0]
	v_pk_add_f32 v[120:121], v[120:121], 1.0 op_sel_hi:[1,0]
	v_pk_add_f32 v[122:123], v[122:123], 1.0 op_sel_hi:[1,0]
	v_add_f32_e32 v117, 1.0, v117
	v_rcp_f32_e32 v118, v118
	v_rcp_f32_e32 v119, v119
	v_rcp_f32_e32 v120, v120
	v_rcp_f32_e32 v121, v121
	v_rcp_f32_e32 v122, v122
	v_rcp_f32_e32 v123, v123
	v_add_f32_e32 v124, 1.0, v124
	v_rcp_f32_e32 v117, v117
	v_rcp_f32_e32 v124, v124
	v_mul_f32_e32 v118, v111, v118
	v_mul_f32_e32 v119, v112, v119
	v_mul_f32_e32 v120, v113, v120
	v_mul_f32_e32 v121, v106, v121
	v_mul_f32_e32 v122, v107, v122
	v_mul_f32_e32 v123, v108, v123
	v_mul_f32_e32 v117, v110, v117
	v_mul_f32_e32 v124, v109, v124
	v_cvt_pk_bf16_f32 v118, v117, v118
	v_cvt_pk_bf16_f32 v119, v119, v120
	v_cvt_pk_bf16_f32 v120, v121, v122
	v_cvt_pk_bf16_f32 v121, v123, v124
	v_lshl_add_u64 v[122:123], v[114:115], 1, s[22:23]
	s_mov_b64 s[86:87], 0
	global_store_dwordx4 v[122:123], v[118:121], off

; __device__ __forceinline__ unsigned cvt_pk_bf16(float lo, float hi) { unsigned r; asm volatile("v_cvt_pk_bf16_f32 %0, %1, %2" : "=v"(r) : "v"(lo), "v"(hi)); return r; }
; __device__ __forceinline__ float siluf(float x) { return x * __builtin_amdgcn_rcpf(1.f + __expf(-x)); }
; __device__ __forceinline__ float logf_of(float p, float lb) { const float sig = __builtin_amdgcn_rcpf(1.f + __expf(-p)); const float f = lb + (1.f - lb) * sig; return fmaxf(__logf(f), -60.f); }
; __device__ __forceinline__ void store_wt(void* p, const u32x4 v) { asm volatile("global_store_dwordx4 %0, %1, off sc1\n\ts_nop 2" :: "v"(p), "v"(v) : "memory"); }
; __device__ __forceinline__ u32x4 pack8(const f32x4 a, const f32x4 b) { u32x4 w; w.x = cvt_pk_bf16(a.x, a.y); w.y = cvt_pk_bf16(a.z, a.w); w.z = cvt_pk_bf16(b.x, b.y); w.w = cvt_pk_bf16(b.z, b.w); return w; }
; __device__ __forceinline__ f32x4 silu4(const f32x4 p) { f32x4 r; r.x = siluf(p.x); r.y = siluf(p.y); r.z = siluf(p.z); r.w = siluf(p.w); return r; }
;     __device__ __forceinline__ void operator()(f32x4 (&acc)[2][2][4][2], const pg8::Unit& u, int ui, int wr, int wc, int fr, int fq) const {
;     ...
;                     if (grp == 0) { *(u32x4*)(Q + o) = pack8(silu4(p0) * QSCALE, silu4(p1) * QSCALE); }
;                     else if (grp == 1) { f32x4 l0, l1; l0.x = logf_of(p0.x, lb[bj][0].x); l0.y = logf_of(p0.y, lb[bj][0].y); l0.z = logf_of(p0.z, lb[bj][0].z); l0.w = logf_of(p0.w, lb[bj][0].w);
;                         l1.x = logf_of(p1.x, lb[bj][1].x); l1.y = logf_of(p1.y, lb[bj][1].y); l1.z = logf_of(p1.z, lb[bj][1].z); l1.w = logf_of(p1.w, lb[bj][1].w);
;                         const f32x8_t ff = {l0.x, l0.y, l0.z, l0.w, l1.x, l1.y, l1.z, l1.w}; *(f16x8_t*)(LF + o) = __builtin_convertvector(ff, f16x8_t); }
;                     else if (grp == 2) { *(u32x4*)(V + o) = pack8(p0, p1); }
;                     else if (grp == 3) { *(u32x4*)(SG + o) = pack8(silu4(p0), silu4(p1)); }
;                     else { store_wt(U + o, pack8(p0, p1)); }
.LBB0_549:
	s_cmp_gt_i32 s29, 2
	s_cbranch_scc0 .LBB0_553
	s_cmp_eq_u32 s29, 3
	s_mov_b64 s[86:87], -1
	s_cbranch_scc0 .LBB0_552
	v_pk_mul_f32 v[108:109], v[106:107], s[100:101] op_sel_hi:[1,0]
	v_mul_f32_e32 v110, 0xbfb8aa3b, v104
	v_pk_mul_f32 v[112:113], v[102:103], s[100:101] op_sel_hi:[1,0]
	v_exp_f32_e32 v108, v108
	v_exp_f32_e32 v109, v109
	v_exp_f32_e32 v110, v110
	v_mul_f32_e32 v111, 0xbfb8aa3b, v105
	v_exp_f32_e32 v112, v112
	v_exp_f32_e32 v113, v113
	v_exp_f32_e32 v111, v111
	v_pk_mul_f32 v[116:117], v[100:101], s[100:101] op_sel_hi:[1,0]
	v_exp_f32_e32 v116, v116
	v_exp_f32_e32 v117, v117
	v_pk_add_f32 v[108:109], v[108:109], 1.0 op_sel_hi:[1,0]
	v_add_f32_e32 v110, 1.0, v110
	v_pk_add_f32 v[112:113], v[112:113], 1.0 op_sel_hi:[1,0]
	v_rcp_f32_e32 v108, v108
	v_rcp_f32_e32 v109, v109
	v_rcp_f32_e32 v110, v110
	v_add_f32_e32 v111, 1.0, v111
	v_rcp_f32_e32 v112, v112
	v_rcp_f32_e32 v113, v113
	v_rcp_f32_e32 v111, v111
	v_pk_add_f32 v[116:117], v[116:117], 1.0 op_sel_hi:[1,0]
	v_rcp_f32_e32 v116, v116
	v_rcp_f32_e32 v117, v117
	v_mul_f32_e32 v108, v106, v108
	v_mul_f32_e32 v109, v107, v109
	v_mul_f32_e32 v110, v104, v110
	v_mul_f32_e32 v112, v102, v112
	v_mul_f32_e32 v113, v103, v113
	v_mul_f32_e32 v111, v105, v111
	v_cvt_pk_bf16_f32 v108, v108, v109
	v_cvt_pk_bf16_f32 v109, v110, v111
	v_cvt_pk_bf16_f32 v110, v112, v113
	v_lshl_add_u64 v[112:113], v[98:99], 1, s[22:23]
	s_mov_b64 s[86:87], 0
	v_mul_f32_e32 v116, v100, v116
	v_mul_f32_e32 v117, v101, v117
	v_cvt_pk_bf16_f32 v111, v116, v117
	global_store_dwordx4 v[112:113], v[108:111], off

; __device__ __forceinline__ unsigned cvt_pk_bf16(float lo, float hi) { unsigned r; asm volatile("v_cvt_pk_bf16_f32 %0, %1, %2" : "=v"(r) : "v"(lo), "v"(hi)); return r; }
; __device__ __forceinline__ float siluf(float x) { return x * __builtin_amdgcn_rcpf(1.f + __expf(-x)); }
; __device__ __forceinline__ float logf_of(float p, float lb) { const float sig = __builtin_amdgcn_rcpf(1.f + __expf(-p)); const float f = lb + (1.f - lb) * sig; return fmaxf(__logf(f), -60.f); }
; __device__ __forceinline__ void store_wt(void* p, const u32x4 v) { asm volatile("global_store_dwordx4 %0, %1, off sc1\n\ts_nop 2" :: "v"(p), "v"(v) : "memory"); }
; __device__ __forceinline__ u32x4 pack8(const f32x4 a, const f32x4 b) { u32x4 w; w.x = cvt_pk_bf16(a.x, a.y); w.y = cvt_pk_bf16(a.z, a.w); w.z = cvt_pk_bf16(b.x, b.y); w.w = cvt_pk_bf16(b.z, b.w); return w; }
; __device__ __forceinline__ f32x4 silu4(const f32x4 p) { f32x4 r; r.x = siluf(p.x); r.y = siluf(p.y); r.z = siluf(p.z); r.w = siluf(p.w); return r; }
;     __device__ __forceinline__ void operator()(f32x4 (&acc)[2][2][4][2], const pg8::Unit& u, int ui, int wr, int wc, int fr, int fq) const {
;     ...
;                     if (grp == 0) { *(u32x4*)(Q + o) = pack8(silu4(p0) * QSCALE, silu4(p1) * QSCALE); }
;                     else if (grp == 1) { f32x4 l0, l1; l0.x = logf_of(p0.x, lb[bj][0].x); l0.y = logf_of(p0.y, lb[bj][0].y); l0.z = logf_of(p0.z, lb[bj][0].z); l0.w = logf_of(p0.w, lb[bj][0].w);
;                         l1.x = logf_of(p1.x, lb[bj][1].x); l1.y = logf_of(p1.y, lb[bj][1].y); l1.z = logf_of(p1.z, lb[bj][1].z); l1.w = logf_of(p1.w, lb[bj][1].w);
;                         const f32x8_t ff = {l0.x, l0.y, l0.z, l0.w, l1.x, l1.y, l1.z, l1.w}; *(f16x8_t*)(LF + o) = __builtin_convertvector(ff, f16x8_t); }
;                     else if (grp == 2) { *(u32x4*)(V + o) = pack8(p0, p1); }
;                     else if (grp == 3) { *(u32x4*)(SG + o) = pack8(silu4(p0), silu4(p1)); }
;                     else { store_wt(U + o, pack8(p0, p1)); }
.LBB0_558:
	s_cmp_gt_i32 s29, 2
	s_cbranch_scc0 .LBB0_562
	s_cmp_eq_u32 s29, 3
	s_mov_b64 s[86:87], -1
	s_cbranch_scc0 .LBB0_561
	v_mul_f32_e32 v102, 0xbfb8aa3b, v95
	v_mul_f32_e32 v103, 0xbfb8aa3b, v96
	v_mul_f32_e32 v104, 0xbfb8aa3b, v97
	v_mul_f32_e32 v105, 0xbfb8aa3b, v90
	v_mul_f32_e32 v106, 0xbfb8aa3b, v91
	v_mul_f32_e32 v107, 0xbfb8aa3b, v92
	v_mul_f32_e32 v101, 0xbfb8aa3b, v94
	v_exp_f32_e32 v102, v102
	v_exp_f32_e32 v103, v103
	v_exp_f32_e32 v104, v104
	v_exp_f32_e32 v105, v105
	v_exp_f32_e32 v106, v106
	v_exp_f32_e32 v107, v107
	v_mul_f32_e32 v108, 0xbfb8aa3b, v93
	v_exp_f32_e32 v101, v101
	v_exp_f32_e32 v108, v108
	v_pk_add_f32 v[102:103], v[102:103], 1.0 op_sel_hi:[1,0]
	v_pk_add_f32 v[104:105], v[104:105], 1.0 op_sel_hi:[1,0]
	v_pk_add_f32 v[106:107], v[106:107], 1.0 op_sel_hi:[1,0]
	v_add_f32_e32 v101, 1.0, v101
	v_rcp_f32_e32 v102, v102
	v_rcp_f32_e32 v103, v103
	v_rcp_f32_e32 v104, v104
	v_rcp_f32_e32 v105, v105
	v_rcp_f32_e32 v106, v106
	v_rcp_f32_e32 v107, v107
	v_add_f32_e32 v108, 1.0, v108
	v_rcp_f32_e32 v101, v101
	v_rcp_f32_e32 v108, v108
	v_mul_f32_e32 v102, v95, v102
	v_mul_f32_e32 v103, v96, v103
	v_mul_f32_e32 v104, v97, v104
	v_mul_f32_e32 v105, v90, v105
	v_mul_f32_e32 v106, v91, v106
	v_mul_f32_e32 v107, v92, v107
	v_mul_f32_e32 v101, v94, v101
	v_mul_f32_e32 v108, v93, v108
	v_cvt_pk_bf16_f32 v102, v101, v102
	v_cvt_pk_bf16_f32 v103, v103, v104
	v_cvt_pk_bf16_f32 v104, v105, v106
	v_cvt_pk_bf16_f32 v105, v107, v108
	v_lshl_add_u64 v[106:107], v[98:99], 1, s[22:23]
	s_mov_b64 s[86:87], 0
	global_store_dwordx4 v[106:107], v[102:105], off

; __device__ __forceinline__ unsigned cvt_pk_bf16(float lo, float hi) { unsigned r; asm volatile("v_cvt_pk_bf16_f32 %0, %1, %2" : "=v"(r) : "v"(lo), "v"(hi)); return r; }
; __device__ __forceinline__ float siluf(float x) { return x * __builtin_amdgcn_rcpf(1.f + __expf(-x)); }
; __device__ __forceinline__ float logf_of(float p, float lb) { const float sig = __builtin_amdgcn_rcpf(1.f + __expf(-p)); const float f = lb + (1.f - lb) * sig; return fmaxf(__logf(f), -60.f); }
; __device__ __forceinline__ void store_wt(void* p, const u32x4 v) { asm volatile("global_store_dwordx4 %0, %1, off sc1\n\ts_nop 2" :: "v"(p), "v"(v) : "memory"); }
; __device__ __forceinline__ u32x4 pack8(const f32x4 a, const f32x4 b) { u32x4 w; w.x = cvt_pk_bf16(a.x, a.y); w.y = cvt_pk_bf16(a.z, a.w); w.z = cvt_pk_bf16(b.x, b.y); w.w = cvt_pk_bf16(b.z, b.w); return w; }
; __device__ __forceinline__ f32x4 silu4(const f32x4 p) { f32x4 r; r.x = siluf(p.x); r.y = siluf(p.y); r.z = siluf(p.z); r.w = siluf(p.w); return r; }
;     __device__ __forceinline__ void operator()(f32x4 (&acc)[2][2][4][2], const pg8::Unit& u, int ui, int wr, int wc, int fr, int fq) const {
;     ...
;                     if (grp == 0) { *(u32x4*)(Q + o) = pack8(silu4(p0) * QSCALE, silu4(p1) * QSCALE); }
;                     else if (grp == 1) { f32x4 l0, l1; l0.x = logf_of(p0.x, lb[bj][0].x); l0.y = logf_of(p0.y, lb[bj][0].y); l0.z = logf_of(p0.z, lb[bj][0].z); l0.w = logf_of(p0.w, lb[bj][0].w);
;                         l1.x = logf_of(p1.x, lb[bj][1].x); l1.y = logf_of(p1.y, lb[bj][1].y); l1.z = logf_of(p1.z, lb[bj][1].z); l1.w = logf_of(p1.w, lb[bj][1].w);
;                         const f32x8_t ff = {l0.x, l0.y, l0.z, l0.w, l1.x, l1.y, l1.z, l1.w}; *(f16x8_t*)(LF + o) = __builtin_convertvector(ff, f16x8_t); }
;                     else if (grp == 2) { *(u32x4*)(V + o) = pack8(p0, p1); }
;                     else if (grp == 3) { *(u32x4*)(SG + o) = pack8(silu4(p0), silu4(p1)); }
;                     else { store_wt(U + o, pack8(p0, p1)); }
.LBB0_567:
	s_cmp_gt_i32 s29, 2
	s_cbranch_scc0 .LBB0_571
	s_cmp_eq_u32 s29, 3
	s_mov_b64 s[86:87], -1
	s_cbranch_scc0 .LBB0_570
	v_pk_mul_f32 v[92:93], v[90:91], s[100:101] op_sel_hi:[1,0]
	v_mul_f32_e32 v94, 0xbfb8aa3b, v88
	v_pk_mul_f32 v[96:97], v[86:87], s[100:101] op_sel_hi:[1,0]
	v_exp_f32_e32 v92, v92
	v_exp_f32_e32 v93, v93
	v_exp_f32_e32 v94, v94
	v_mul_f32_e32 v95, 0xbfb8aa3b, v89
	v_exp_f32_e32 v96, v96
	v_exp_f32_e32 v97, v97
	v_exp_f32_e32 v95, v95
	v_pk_mul_f32 v[100:101], v[84:85], s[100:101] op_sel_hi:[1,0]
	v_exp_f32_e32 v100, v100
	v_exp_f32_e32 v101, v101
	v_pk_add_f32 v[92:93], v[92:93], 1.0 op_sel_hi:[1,0]
	v_add_f32_e32 v94, 1.0, v94
	v_pk_add_f32 v[96:97], v[96:97], 1.0 op_sel_hi:[1,0]
	v_rcp_f32_e32 v92, v92
	v_rcp_f32_e32 v93, v93
	v_rcp_f32_e32 v94, v94
	v_add_f32_e32 v95, 1.0, v95
	v_rcp_f32_e32 v96, v96
	v_rcp_f32_e32 v97, v97
	v_rcp_f32_e32 v95, v95
	v_pk_add_f32 v[100:101], v[100:101], 1.0 op_sel_hi:[1,0]
	v_rcp_f32_e32 v100, v100
	v_rcp_f32_e32 v101, v101
	v_mul_f32_e32 v92, v90, v92
	v_mul_f32_e32 v93, v91, v93
	v_mul_f32_e32 v94, v88, v94
	v_mul_f32_e32 v96, v86, v96
	v_mul_f32_e32 v97, v87, v97
	v_mul_f32_e32 v95, v89, v95
	v_cvt_pk_bf16_f32 v92, v92, v93
	v_cvt_pk_bf16_f32 v93, v94, v95
	v_cvt_pk_bf16_f32 v94, v96, v97
	v_lshl_add_u64 v[96:97], v[82:83], 1, s[22:23]
	s_mov_b64 s[86:87], 0
	v_mul_f32_e32 v100, v84, v100
	v_mul_f32_e32 v101, v85, v101
	v_cvt_pk_bf16_f32 v95, v100, v101
	global_store_dwordx4 v[96:97], v[92:95], off

; __device__ __forceinline__ unsigned cvt_pk_bf16(float lo, float hi) { unsigned r; asm volatile("v_cvt_pk_bf16_f32 %0, %1, %2" : "=v"(r) : "v"(lo), "v"(hi)); return r; }
; __device__ __forceinline__ float siluf(float x) { return x * __builtin_amdgcn_rcpf(1.f + __expf(-x)); }
; __device__ __forceinline__ float logf_of(float p, float lb) { const float sig = __builtin_amdgcn_rcpf(1.f + __expf(-p)); const float f = lb + (1.f - lb) * sig; return fmaxf(__logf(f), -60.f); }
; __device__ __forceinline__ void store_wt(void* p, const u32x4 v) { asm volatile("global_store_dwordx4 %0, %1, off sc1\n\ts_nop 2" :: "v"(p), "v"(v) : "memory"); }
; __device__ __forceinline__ u32x4 pack8(const f32x4 a, const f32x4 b) { u32x4 w; w.x = cvt_pk_bf16(a.x, a.y); w.y = cvt_pk_bf16(a.z, a.w); w.z = cvt_pk_bf16(b.x, b.y); w.w = cvt_pk_bf16(b.z, b.w); return w; }
; __device__ __forceinline__ f32x4 silu4(const f32x4 p) { f32x4 r; r.x = siluf(p.x); r.y = siluf(p.y); r.z = siluf(p.z); r.w = siluf(p.w); return r; }
;     __device__ __forceinline__ void operator()(f32x4 (&acc)[2][2][4][2], const pg8::Unit& u, int ui, int wr, int wc, int fr, int fq) const {
;     ...
;                     if (grp == 0) { *(u32x4*)(Q + o) = pack8(silu4(p0) * QSCALE, silu4(p1) * QSCALE); }
;                     else if (grp == 1) { f32x4 l0, l1; l0.x = logf_of(p0.x, lb[bj][0].x); l0.y = logf_of(p0.y, lb[bj][0].y); l0.z = logf_of(p0.z, lb[bj][0].z); l0.w = logf_of(p0.w, lb[bj][0].w);
;                         l1.x = logf_of(p1.x, lb[bj][1].x); l1.y = logf_of(p1.y, lb[bj][1].y); l1.z = logf_of(p1.z, lb[bj][1].z); l1.w = logf_of(p1.w, lb[bj][1].w);
;                         const f32x8_t ff = {l0.x, l0.y, l0.z, l0.w, l1.x, l1.y, l1.z, l1.w}; *(f16x8_t*)(LF + o) = __builtin_convertvector(ff, f16x8_t); }
;                     else if (grp == 2) { *(u32x4*)(V + o) = pack8(p0, p1); }
;                     else if (grp == 3) { *(u32x4*)(SG + o) = pack8(silu4(p0), silu4(p1)); }
;                     else { store_wt(U + o, pack8(p0, p1)); }
.LBB0_576:
	s_cmp_gt_i32 s29, 2
	s_cbranch_scc0 .LBB0_580
	s_cmp_eq_u32 s29, 3
	s_mov_b64 s[86:87], -1
	s_cbranch_scc0 .LBB0_579
	v_mul_f32_e32 v86, 0xbfb8aa3b, v79
	v_mul_f32_e32 v87, 0xbfb8aa3b, v80
	v_mul_f32_e32 v88, 0xbfb8aa3b, v81
	v_mul_f32_e32 v89, 0xbfb8aa3b, v74
	v_mul_f32_e32 v90, 0xbfb8aa3b, v75
	v_mul_f32_e32 v91, 0xbfb8aa3b, v76
	v_mul_f32_e32 v85, 0xbfb8aa3b, v78
	v_exp_f32_e32 v86, v86
	v_exp_f32_e32 v87, v87
	v_exp_f32_e32 v88, v88
	v_exp_f32_e32 v89, v89
	v_exp_f32_e32 v90, v90
	v_exp_f32_e32 v91, v91
	v_mul_f32_e32 v92, 0xbfb8aa3b, v77
	v_exp_f32_e32 v85, v85
	v_exp_f32_e32 v92, v92
	v_pk_add_f32 v[86:87], v[86:87], 1.0 op_sel_hi:[1,0]
	v_pk_add_f32 v[88:89], v[88:89], 1.0 op_sel_hi:[1,0]
	v_pk_add_f32 v[90:91], v[90:91], 1.0 op_sel_hi:[1,0]
	v_add_f32_e32 v85, 1.0, v85
	v_rcp_f32_e32 v86, v86
	v_rcp_f32_e32 v87, v87
	v_rcp_f32_e32 v88, v88
	v_rcp_f32_e32 v89, v89
	v_rcp_f32_e32 v90, v90
	v_rcp_f32_e32 v91, v91
	v_add_f32_e32 v92, 1.0, v92
	v_rcp_f32_e32 v85, v85
	v_rcp_f32_e32 v92, v92
	v_mul_f32_e32 v86, v79, v86
	v_mul_f32_e32 v87, v80, v87
	v_mul_f32_e32 v88, v81, v88
	v_mul_f32_e32 v89, v74, v89
	v_mul_f32_e32 v90, v75, v90
	v_mul_f32_e32 v91, v76, v91
	v_mul_f32_e32 v85, v78, v85
	v_mul_f32_e32 v92, v77, v92
	v_cvt_pk_bf16_f32 v86, v85, v86
	v_cvt_pk_bf16_f32 v87, v87, v88
	v_cvt_pk_bf16_f32 v88, v89, v90
	v_cvt_pk_bf16_f32 v89, v91, v92
	v_lshl_add_u64 v[90:91], v[82:83], 1, s[22:23]
	s_mov_b64 s[86:87], 0
	global_store_dwordx4 v[90:91], v[86:89], off

; __device__ __forceinline__ unsigned cvt_pk_bf16(float lo, float hi) { unsigned r; asm volatile("v_cvt_pk_bf16_f32 %0, %1, %2" : "=v"(r) : "v"(lo), "v"(hi)); return r; }
; __device__ __forceinline__ float siluf(float x) { return x * __builtin_amdgcn_rcpf(1.f + __expf(-x)); }
; __device__ __forceinline__ float logf_of(float p, float lb) { const float sig = __builtin_amdgcn_rcpf(1.f + __expf(-p)); const float f = lb + (1.f - lb) * sig; return fmaxf(__logf(f), -60.f); }
; __device__ __forceinline__ void store_wt(void* p, const u32x4 v) { asm volatile("global_store_dwordx4 %0, %1, off sc1\n\ts_nop 2" :: "v"(p), "v"(v) : "memory"); }
; __device__ __forceinline__ u32x4 pack8(const f32x4 a, const f32x4 b) { u32x4 w; w.x = cvt_pk_bf16(a.x, a.y); w.y = cvt_pk_bf16(a.z, a.w); w.z = cvt_pk_bf16(b.x, b.y); w.w = cvt_pk_bf16(b.z, b.w); return w; }
; __device__ __forceinline__ f32x4 silu4(const f32x4 p) { f32x4 r; r.x = siluf(p.x); r.y = siluf(p.y); r.z = siluf(p.z); r.w = siluf(p.w); return r; }
;     __device__ __forceinline__ void operator()(f32x4 (&acc)[2][2][4][2], const pg8::Unit& u, int ui, int wr, int wc, int fr, int fq) const {
;     ...
;                     if (grp == 0) { *(u32x4*)(Q + o) = pack8(silu4(p0) * QSCALE, silu4(p1) * QSCALE); }
;                     else if (grp == 1) { f32x4 l0, l1; l0.x = logf_of(p0.x, lb[bj][0].x); l0.y = logf_of(p0.y, lb[bj][0].y); l0.z = logf_of(p0.z, lb[bj][0].z); l0.w = logf_of(p0.w, lb[bj][0].w);
;                         l1.x = logf_of(p1.x, lb[bj][1].x); l1.y = logf_of(p1.y, lb[bj][1].y); l1.z = logf_of(p1.z, lb[bj][1].z); l1.w = logf_of(p1.w, lb[bj][1].w);
;                         const f32x8_t ff = {l0.x, l0.y, l0.z, l0.w, l1.x, l1.y, l1.z, l1.w}; *(f16x8_t*)(LF + o) = __builtin_convertvector(ff, f16x8_t); }
;                     else if (grp == 2) { *(u32x4*)(V + o) = pack8(p0, p1); }
;                     else if (grp == 3) { *(u32x4*)(SG + o) = pack8(silu4(p0), silu4(p1)); }
;                     else { store_wt(U + o, pack8(p0, p1)); }
.LBB0_585:
	s_cmp_gt_i32 s29, 2
	s_cbranch_scc0 .LBB0_589
	s_cmp_eq_u32 s29, 3
	s_mov_b64 s[86:87], -1
	s_cbranch_scc0 .LBB0_588
	v_pk_mul_f32 v[76:77], v[74:75], s[100:101] op_sel_hi:[1,0]
	v_mul_f32_e32 v78, 0xbfb8aa3b, v72
	v_pk_mul_f32 v[80:81], v[70:71], s[100:101] op_sel_hi:[1,0]
	v_exp_f32_e32 v76, v76
	v_exp_f32_e32 v77, v77
	v_exp_f32_e32 v78, v78
	v_mul_f32_e32 v79, 0xbfb8aa3b, v73
	v_exp_f32_e32 v80, v80
	v_exp_f32_e32 v81, v81
	v_exp_f32_e32 v79, v79
	v_pk_mul_f32 v[84:85], v[68:69], s[100:101] op_sel_hi:[1,0]
	v_exp_f32_e32 v84, v84
	v_exp_f32_e32 v85, v85
	v_pk_add_f32 v[76:77], v[76:77], 1.0 op_sel_hi:[1,0]
	v_add_f32_e32 v78, 1.0, v78
	v_pk_add_f32 v[80:81], v[80:81], 1.0 op_sel_hi:[1,0]
	v_rcp_f32_e32 v76, v76
	v_rcp_f32_e32 v77, v77
	v_rcp_f32_e32 v78, v78
	v_add_f32_e32 v79, 1.0, v79
	v_rcp_f32_e32 v80, v80
	v_rcp_f32_e32 v81, v81
	v_rcp_f32_e32 v79, v79
	v_pk_add_f32 v[84:85], v[84:85], 1.0 op_sel_hi:[1,0]
	v_rcp_f32_e32 v84, v84
	v_rcp_f32_e32 v85, v85
	v_mul_f32_e32 v76, v74, v76
	v_mul_f32_e32 v77, v75, v77
	v_mul_f32_e32 v78, v72, v78
	v_mul_f32_e32 v80, v70, v80
	v_mul_f32_e32 v81, v71, v81
	v_mul_f32_e32 v79, v73, v79
	v_cvt_pk_bf16_f32 v76, v76, v77
	v_cvt_pk_bf16_f32 v77, v78, v79
	v_cvt_pk_bf16_f32 v78, v80, v81
	v_lshl_add_u64 v[80:81], v[66:67], 1, s[22:23]
	s_mov_b64 s[86:87], 0
	v_mul_f32_e32 v84, v68, v84
	v_mul_f32_e32 v85, v69, v85
	v_cvt_pk_bf16_f32 v79, v84, v85
	global_store_dwordx4 v[80:81], v[76:79], off

; __device__ __forceinline__ unsigned cvt_pk_bf16(float lo, float hi) { unsigned r; asm volatile("v_cvt_pk_bf16_f32 %0, %1, %2" : "=v"(r) : "v"(lo), "v"(hi)); return r; }
; __device__ __forceinline__ float siluf(float x) { return x * __builtin_amdgcn_rcpf(1.f + __expf(-x)); }
; __device__ __forceinline__ float logf_of(float p, float lb) { const float sig = __builtin_amdgcn_rcpf(1.f + __expf(-p)); const float f = lb + (1.f - lb) * sig; return fmaxf(__logf(f), -60.f); }
; __device__ __forceinline__ void store_wt(void* p, const u32x4 v) { asm volatile("global_store_dwordx4 %0, %1, off sc1\n\ts_nop 2" :: "v"(p), "v"(v) : "memory"); }
; __device__ __forceinline__ u32x4 pack8(const f32x4 a, const f32x4 b) { u32x4 w; w.x = cvt_pk_bf16(a.x, a.y); w.y = cvt_pk_bf16(a.z, a.w); w.z = cvt_pk_bf16(b.x, b.y); w.w = cvt_pk_bf16(b.z, b.w); return w; }
; __device__ __forceinline__ f32x4 silu4(const f32x4 p) { f32x4 r; r.x = siluf(p.x); r.y = siluf(p.y); r.z = siluf(p.z); r.w = siluf(p.w); return r; }
;     __device__ __forceinline__ void operator()(f32x4 (&acc)[2][2][4][2], const pg8::Unit& u, int ui, int wr, int wc, int fr, int fq) const {
;     ...
;                     if (grp == 0) { *(u32x4*)(Q + o) = pack8(silu4(p0) * QSCALE, silu4(p1) * QSCALE); }
;                     else if (grp == 1) { f32x4 l0, l1; l0.x = logf_of(p0.x, lb[bj][0].x); l0.y = logf_of(p0.y, lb[bj][0].y); l0.z = logf_of(p0.z, lb[bj][0].z); l0.w = logf_of(p0.w, lb[bj][0].w);
;                         l1.x = logf_of(p1.x, lb[bj][1].x); l1.y = logf_of(p1.y, lb[bj][1].y); l1.z = logf_of(p1.z, lb[bj][1].z); l1.w = logf_of(p1.w, lb[bj][1].w);
;                         const f32x8_t ff = {l0.x, l0.y, l0.z, l0.w, l1.x, l1.y, l1.z, l1.w}; *(f16x8_t*)(LF + o) = __builtin_convertvector(ff, f16x8_t); }
;                     else if (grp == 2) { *(u32x4*)(V + o) = pack8(p0, p1); }
;                     else if (grp == 3) { *(u32x4*)(SG + o) = pack8(silu4(p0), silu4(p1)); }
;                     else { store_wt(U + o, pack8(p0, p1)); }
.LBB0_594:
	s_cmp_gt_i32 s29, 2
	s_cbranch_scc0 .LBB0_598
	s_cmp_eq_u32 s29, 3
	s_mov_b64 s[86:87], -1
	s_cbranch_scc0 .LBB0_597
	v_mul_f32_e32 v70, 0xbfb8aa3b, v63
	v_mul_f32_e32 v71, 0xbfb8aa3b, v64
	v_mul_f32_e32 v72, 0xbfb8aa3b, v65
	v_mul_f32_e32 v73, 0xbfb8aa3b, v58
	v_mul_f32_e32 v74, 0xbfb8aa3b, v59
	v_mul_f32_e32 v75, 0xbfb8aa3b, v60
	v_mul_f32_e32 v69, 0xbfb8aa3b, v62
	v_exp_f32_e32 v70, v70
	v_exp_f32_e32 v71, v71
	v_exp_f32_e32 v72, v72
	v_exp_f32_e32 v73, v73
	v_exp_f32_e32 v74, v74
	v_exp_f32_e32 v75, v75
	v_mul_f32_e32 v76, 0xbfb8aa3b, v61
	v_exp_f32_e32 v69, v69
	v_exp_f32_e32 v76, v76
	v_pk_add_f32 v[70:71], v[70:71], 1.0 op_sel_hi:[1,0]
	v_pk_add_f32 v[72:73], v[72:73], 1.0 op_sel_hi:[1,0]
	v_pk_add_f32 v[74:75], v[74:75], 1.0 op_sel_hi:[1,0]
	v_add_f32_e32 v69, 1.0, v69
	v_rcp_f32_e32 v70, v70
	v_rcp_f32_e32 v71, v71
	v_rcp_f32_e32 v72, v72
	v_rcp_f32_e32 v73, v73
	v_rcp_f32_e32 v74, v74
	v_rcp_f32_e32 v75, v75
	v_add_f32_e32 v76, 1.0, v76
	v_rcp_f32_e32 v69, v69
	v_rcp_f32_e32 v76, v76
	v_mul_f32_e32 v70, v63, v70
	v_mul_f32_e32 v71, v64, v71
	v_mul_f32_e32 v72, v65, v72
	v_mul_f32_e32 v73, v58, v73
	v_mul_f32_e32 v74, v59, v74
	v_mul_f32_e32 v75, v60, v75
	v_mul_f32_e32 v69, v62, v69
	v_mul_f32_e32 v76, v61, v76
	v_cvt_pk_bf16_f32 v70, v69, v70
	v_cvt_pk_bf16_f32 v71, v71, v72
	v_cvt_pk_bf16_f32 v72, v73, v74
	v_cvt_pk_bf16_f32 v73, v75, v76
	v_lshl_add_u64 v[74:75], v[66:67], 1, s[22:23]
	s_mov_b64 s[86:87], 0
	global_store_dwordx4 v[74:75], v[70:73], off

; __device__ __forceinline__ unsigned cvt_pk_bf16(float lo, float hi) { unsigned r; asm volatile("v_cvt_pk_bf16_f32 %0, %1, %2" : "=v"(r) : "v"(lo), "v"(hi)); return r; }
; __device__ __forceinline__ float siluf(float x) { return x * __builtin_amdgcn_rcpf(1.f + __expf(-x)); }
; __device__ __forceinline__ float logf_of(float p, float lb) { const float sig = __builtin_amdgcn_rcpf(1.f + __expf(-p)); const float f = lb + (1.f - lb) * sig; return fmaxf(__logf(f), -60.f); }
; __device__ __forceinline__ void store_wt(void* p, const u32x4 v) { asm volatile("global_store_dwordx4 %0, %1, off sc1\n\ts_nop 2" :: "v"(p), "v"(v) : "memory"); }
; __device__ __forceinline__ u32x4 pack8(const f32x4 a, const f32x4 b) { u32x4 w; w.x = cvt_pk_bf16(a.x, a.y); w.y = cvt_pk_bf16(a.z, a.w); w.z = cvt_pk_bf16(b.x, b.y); w.w = cvt_pk_bf16(b.z, b.w); return w; }
; __device__ __forceinline__ f32x4 silu4(const f32x4 p) { f32x4 r; r.x = siluf(p.x); r.y = siluf(p.y); r.z = siluf(p.z); r.w = siluf(p.w); return r; }
;     __device__ __forceinline__ void operator()(f32x4 (&acc)[2][2][4][2], const pg8::Unit& u, int ui, int wr, int wc, int fr, int fq) const {
;     ...
;                     if (grp == 0) { *(u32x4*)(Q + o) = pack8(silu4(p0) * QSCALE, silu4(p1) * QSCALE); }
;                     else if (grp == 1) { f32x4 l0, l1; l0.x = logf_of(p0.x, lb[bj][0].x); l0.y = logf_of(p0.y, lb[bj][0].y); l0.z = logf_of(p0.z, lb[bj][0].z); l0.w = logf_of(p0.w, lb[bj][0].w);
;                         l1.x = logf_of(p1.x, lb[bj][1].x); l1.y = logf_of(p1.y, lb[bj][1].y); l1.z = logf_of(p1.z, lb[bj][1].z); l1.w = logf_of(p1.w, lb[bj][1].w);
;                         const f32x8_t ff = {l0.x, l0.y, l0.z, l0.w, l1.x, l1.y, l1.z, l1.w}; *(f16x8_t*)(LF + o) = __builtin_convertvector(ff, f16x8_t); }
;                     else if (grp == 2) { *(u32x4*)(V + o) = pack8(p0, p1); }
;                     else if (grp == 3) { *(u32x4*)(SG + o) = pack8(silu4(p0), silu4(p1)); }
;                     else { store_wt(U + o, pack8(p0, p1)); }
.LBB0_603:
	s_cmp_gt_i32 s29, 2
	s_cbranch_scc0 .LBB0_607
	s_cmp_eq_u32 s29, 3
	s_mov_b64 s[86:87], -1
	s_cbranch_scc0 .LBB0_606
	v_pk_mul_f32 v[60:61], v[58:59], s[100:101] op_sel_hi:[1,0]
	v_mul_f32_e32 v62, 0xbfb8aa3b, v48
	v_pk_mul_f32 v[64:65], v[46:47], s[100:101] op_sel_hi:[1,0]
	v_exp_f32_e32 v60, v60
	v_exp_f32_e32 v61, v61
	v_exp_f32_e32 v62, v62
	v_mul_f32_e32 v63, 0xbfb8aa3b, v49
	v_exp_f32_e32 v64, v64
	v_exp_f32_e32 v65, v65
	v_exp_f32_e32 v63, v63
	v_pk_mul_f32 v[68:69], v[44:45], s[100:101] op_sel_hi:[1,0]
	v_exp_f32_e32 v68, v68
	v_exp_f32_e32 v69, v69
	v_pk_add_f32 v[60:61], v[60:61], 1.0 op_sel_hi:[1,0]
	v_add_f32_e32 v62, 1.0, v62
	v_pk_add_f32 v[64:65], v[64:65], 1.0 op_sel_hi:[1,0]
	v_rcp_f32_e32 v60, v60
	v_rcp_f32_e32 v61, v61
	v_rcp_f32_e32 v62, v62
	v_add_f32_e32 v63, 1.0, v63
	v_rcp_f32_e32 v64, v64
	v_rcp_f32_e32 v65, v65
	v_rcp_f32_e32 v63, v63
	v_pk_add_f32 v[68:69], v[68:69], 1.0 op_sel_hi:[1,0]
	v_rcp_f32_e32 v68, v68
	v_rcp_f32_e32 v69, v69
	v_mul_f32_e32 v60, v58, v60
	v_mul_f32_e32 v61, v59, v61
	v_mul_f32_e32 v62, v48, v62
	v_mul_f32_e32 v64, v46, v64
	v_mul_f32_e32 v65, v47, v65
	v_mul_f32_e32 v63, v49, v63
	v_cvt_pk_bf16_f32 v60, v60, v61
	v_cvt_pk_bf16_f32 v61, v62, v63
	v_cvt_pk_bf16_f32 v62, v64, v65
	v_lshl_add_u64 v[64:65], v[42:43], 1, s[22:23]
	s_mov_b64 s[86:87], 0
	v_mul_f32_e32 v68, v44, v68
	v_mul_f32_e32 v69, v45, v69
	v_cvt_pk_bf16_f32 v63, v68, v69
	global_store_dwordx4 v[64:65], v[60:63], off

; __device__ __forceinline__ unsigned cvt_pk_bf16(float lo, float hi) { unsigned r; asm volatile("v_cvt_pk_bf16_f32 %0, %1, %2" : "=v"(r) : "v"(lo), "v"(hi)); return r; }
; __device__ __forceinline__ float siluf(float x) { return x * __builtin_amdgcn_rcpf(1.f + __expf(-x)); }
; __device__ __forceinline__ float logf_of(float p, float lb) { const float sig = __builtin_amdgcn_rcpf(1.f + __expf(-p)); const float f = lb + (1.f - lb) * sig; return fmaxf(__logf(f), -60.f); }
; __device__ __forceinline__ void store_wt(void* p, const u32x4 v) { asm volatile("global_store_dwordx4 %0, %1, off sc1\n\ts_nop 2" :: "v"(p), "v"(v) : "memory"); }
; __device__ __forceinline__ u32x4 pack8(const f32x4 a, const f32x4 b) { u32x4 w; w.x = cvt_pk_bf16(a.x, a.y); w.y = cvt_pk_bf16(a.z, a.w); w.z = cvt_pk_bf16(b.x, b.y); w.w = cvt_pk_bf16(b.z, b.w); return w; }
; __device__ __forceinline__ f32x4 silu4(const f32x4 p) { f32x4 r; r.x = siluf(p.x); r.y = siluf(p.y); r.z = siluf(p.z); r.w = siluf(p.w); return r; }
;     __device__ __forceinline__ void operator()(f32x4 (&acc)[2][2][4][2], const pg8::Unit& u, int ui, int wr, int wc, int fr, int fq) const {
;     ...
;                     if (grp == 0) { *(u32x4*)(Q + o) = pack8(silu4(p0) * QSCALE, silu4(p1) * QSCALE); }
;                     else if (grp == 1) { f32x4 l0, l1; l0.x = logf_of(p0.x, lb[bj][0].x); l0.y = logf_of(p0.y, lb[bj][0].y); l0.z = logf_of(p0.z, lb[bj][0].z); l0.w = logf_of(p0.w, lb[bj][0].w);
;                         l1.x = logf_of(p1.x, lb[bj][1].x); l1.y = logf_of(p1.y, lb[bj][1].y); l1.z = logf_of(p1.z, lb[bj][1].z); l1.w = logf_of(p1.w, lb[bj][1].w);
;                         const f32x8_t ff = {l0.x, l0.y, l0.z, l0.w, l1.x, l1.y, l1.z, l1.w}; *(f16x8_t*)(LF + o) = __builtin_convertvector(ff, f16x8_t); }
;                     else if (grp == 2) { *(u32x4*)(V + o) = pack8(p0, p1); }
;                     else if (grp == 3) { *(u32x4*)(SG + o) = pack8(silu4(p0), silu4(p1)); }
;                     else { store_wt(U + o, pack8(p0, p1)); }
.LBB0_612:
	s_cmp_gt_i32 s29, 2
	s_cbranch_scc0 .LBB0_616
	s_cmp_eq_u32 s29, 3
	s_mov_b64 s[86:87], -1
	s_cbranch_scc0 .LBB0_615
	v_mul_f32_e32 v46, 0xbfb8aa3b, v35
	v_mul_f32_e32 v47, 0xbfb8aa3b, v36
	v_mul_f32_e32 v48, 0xbfb8aa3b, v37
	v_mul_f32_e32 v49, 0xbfb8aa3b, v30
	v_mul_f32_e32 v50, 0xbfb8aa3b, v31
	v_mul_f32_e32 v51, 0xbfb8aa3b, v32
	v_mul_f32_e32 v45, 0xbfb8aa3b, v34
	v_exp_f32_e32 v46, v46
	v_exp_f32_e32 v47, v47
	v_exp_f32_e32 v48, v48
	v_exp_f32_e32 v49, v49
	v_exp_f32_e32 v50, v50
	v_exp_f32_e32 v51, v51
	v_mul_f32_e32 v52, 0xbfb8aa3b, v33
	v_exp_f32_e32 v45, v45
	v_exp_f32_e32 v52, v52
	v_pk_add_f32 v[46:47], v[46:47], 1.0 op_sel_hi:[1,0]
	v_pk_add_f32 v[48:49], v[48:49], 1.0 op_sel_hi:[1,0]
	v_pk_add_f32 v[50:51], v[50:51], 1.0 op_sel_hi:[1,0]
	v_add_f32_e32 v45, 1.0, v45
	v_rcp_f32_e32 v46, v46
	v_rcp_f32_e32 v47, v47
	v_rcp_f32_e32 v48, v48
	v_rcp_f32_e32 v49, v49
	v_rcp_f32_e32 v50, v50
	v_rcp_f32_e32 v51, v51
	v_add_f32_e32 v52, 1.0, v52
	v_rcp_f32_e32 v45, v45
	v_rcp_f32_e32 v52, v52
	v_mul_f32_e32 v46, v35, v46
	v_mul_f32_e32 v47, v36, v47
	v_mul_f32_e32 v48, v37, v48
	v_mul_f32_e32 v49, v30, v49
	v_mul_f32_e32 v50, v31, v50
	v_mul_f32_e32 v51, v32, v51
	v_mul_f32_e32 v45, v34, v45
	v_mul_f32_e32 v52, v33, v52
	v_cvt_pk_bf16_f32 v46, v45, v46
	v_cvt_pk_bf16_f32 v47, v47, v48
	v_cvt_pk_bf16_f32 v48, v49, v50
	v_cvt_pk_bf16_f32 v49, v51, v52
	v_lshl_add_u64 v[50:51], v[42:43], 1, s[22:23]
	s_mov_b64 s[86:87], 0
	global_store_dwordx4 v[50:51], v[46:49], off

; __device__ __forceinline__ unsigned cvt_pk_bf16(float lo, float hi) { unsigned r; asm volatile("v_cvt_pk_bf16_f32 %0, %1, %2" : "=v"(r) : "v"(lo), "v"(hi)); return r; }
; __device__ __forceinline__ float siluf(float x) { return x * __builtin_amdgcn_rcpf(1.f + __expf(-x)); }
; __device__ __forceinline__ float logf_of(float p, float lb) { const float sig = __builtin_amdgcn_rcpf(1.f + __expf(-p)); const float f = lb + (1.f - lb) * sig; return fmaxf(__logf(f), -60.f); }
; __device__ __forceinline__ void store_wt(void* p, const u32x4 v) { asm volatile("global_store_dwordx4 %0, %1, off sc1\n\ts_nop 2" :: "v"(p), "v"(v) : "memory"); }
; __device__ __forceinline__ u32x4 pack8(const f32x4 a, const f32x4 b) { u32x4 w; w.x = cvt_pk_bf16(a.x, a.y); w.y = cvt_pk_bf16(a.z, a.w); w.z = cvt_pk_bf16(b.x, b.y); w.w = cvt_pk_bf16(b.z, b.w); return w; }
; __device__ __forceinline__ f32x4 silu4(const f32x4 p) { f32x4 r; r.x = siluf(p.x); r.y = siluf(p.y); r.z = siluf(p.z); r.w = siluf(p.w); return r; }
;     __device__ __forceinline__ void operator()(f32x4 (&acc)[2][2][4][2], const pg8::Unit& u, int ui, int wr, int wc, int fr, int fq) const {
;     ...
;                     if (grp == 0) { *(u32x4*)(Q + o) = pack8(silu4(p0) * QSCALE, silu4(p1) * QSCALE); }
;                     else if (grp == 1) { f32x4 l0, l1; l0.x = logf_of(p0.x, lb[bj][0].x); l0.y = logf_of(p0.y, lb[bj][0].y); l0.z = logf_of(p0.z, lb[bj][0].z); l0.w = logf_of(p0.w, lb[bj][0].w);
;                         l1.x = logf_of(p1.x, lb[bj][1].x); l1.y = logf_of(p1.y, lb[bj][1].y); l1.z = logf_of(p1.z, lb[bj][1].z); l1.w = logf_of(p1.w, lb[bj][1].w);
;                         const f32x8_t ff = {l0.x, l0.y, l0.z, l0.w, l1.x, l1.y, l1.z, l1.w}; *(f16x8_t*)(LF + o) = __builtin_convertvector(ff, f16x8_t); }
;                     else if (grp == 2) { *(u32x4*)(V + o) = pack8(p0, p1); }
;                     else if (grp == 3) { *(u32x4*)(SG + o) = pack8(silu4(p0), silu4(p1)); }
;                     else { store_wt(U + o, pack8(p0, p1)); }
.LBB0_621:
	s_cmp_gt_i32 s29, 2
	s_cbranch_scc0 .LBB0_625
	s_cmp_eq_u32 s29, 3
	s_mov_b64 s[8:9], -1
	s_cbranch_scc0 .LBB0_624
	v_pk_mul_f32 v[20:21], v[18:19], s[100:101] op_sel_hi:[1,0]
	v_mul_f32_e32 v22, 0xbfb8aa3b, v8
	v_pk_mul_f32 v[24:25], v[6:7], s[100:101] op_sel_hi:[1,0]
	v_exp_f32_e32 v20, v20
	v_exp_f32_e32 v21, v21
	v_exp_f32_e32 v22, v22
	v_mul_f32_e32 v23, 0xbfb8aa3b, v9
	v_exp_f32_e32 v24, v24
	v_exp_f32_e32 v25, v25
	v_exp_f32_e32 v23, v23
	v_pk_mul_f32 v[26:27], v[4:5], s[100:101] op_sel_hi:[1,0]
	v_exp_f32_e32 v26, v26
	v_exp_f32_e32 v27, v27
	v_pk_add_f32 v[20:21], v[20:21], 1.0 op_sel_hi:[1,0]
	v_add_f32_e32 v22, 1.0, v22
	v_pk_add_f32 v[24:25], v[24:25], 1.0 op_sel_hi:[1,0]
	v_rcp_f32_e32 v20, v20
	v_rcp_f32_e32 v21, v21
	v_rcp_f32_e32 v22, v22
	v_add_f32_e32 v23, 1.0, v23
	v_rcp_f32_e32 v24, v24
	v_rcp_f32_e32 v25, v25
	v_rcp_f32_e32 v23, v23
	v_pk_add_f32 v[26:27], v[26:27], 1.0 op_sel_hi:[1,0]
	v_rcp_f32_e32 v26, v26
	v_rcp_f32_e32 v27, v27
	v_mul_f32_e32 v20, v18, v20
	v_mul_f32_e32 v21, v19, v21
	v_mul_f32_e32 v22, v8, v22
	v_mul_f32_e32 v24, v6, v24
	v_mul_f32_e32 v25, v7, v25
	v_mul_f32_e32 v23, v9, v23
	v_cvt_pk_bf16_f32 v20, v20, v21
	v_cvt_pk_bf16_f32 v21, v22, v23
	v_cvt_pk_bf16_f32 v22, v24, v25
	v_lshl_add_u64 v[24:25], v[2:3], 1, s[22:23]
	s_mov_b64 s[8:9], 0
	v_mul_f32_e32 v26, v4, v26
	v_mul_f32_e32 v27, v5, v27
	v_cvt_pk_bf16_f32 v23, v26, v27
	global_store_dwordx4 v[24:25], v[20:23], off

; __device__ __forceinline__ void store_wt(void* p, const u32x4 v) { asm volatile("global_store_dwordx4 %0, %1, off sc1\n\ts_nop 2" :: "v"(p), "v"(v) : "memory"); }
;     __device__ __forceinline__ void operator()(f32x4 (&acc)[2][2][4][2], const pg8::Unit& u, int ui, int wr, int wc, int fr, int fq) const {
;         const int b = u.pm >> 4, lrow = wr * 128 + fr * 8, jc = u.pn * 128 + wc * 32 + fq * 8, swc = u.pn * 256 + wc * 32 + fq * 8;
;         {   f32x4 swa[2], swv[2];
; #pragma unroll
;             for (int n = 0; n < 2; ++n) { swa[n] = *(const f32x4*)(SW + (size_t)b * NUP + swc + n * 4); swv[n] = *(const f32x4*)(SW + (size_t)b * NUP + swc + 128 + n * 4); }
; #pragma unroll
;             for (int ai = 0; ai < 2; ++ai)
; #pragma unroll
;                 for (int m = 0; m < 4; ++m) { const float r = RSTD[ui * 256 + lrow + 4 * ai + m];
; #pragma unroll
;                     for (int n = 0; n < 2; ++n) { acc[ai][0][m][n] = acc[ai][0][m][n] * r + swa[n]; acc[ai][1][m][n] = acc[ai][1][m][n] * r + swv[n]; } }
;         }
;         {   const int kb = u.pm * 2 + wr;
;             if (fr == 0) { float* pa = HA + ((size_t)kb * 4) * DFF + jc; float* pv = HV + ((size_t)kb * 2) * DFF + jc;
;                 *(f32x4*)pa = acc[0][0][0][0]; *(f32x4*)(pa + 4) = acc[0][0][0][1]; *(f32x4*)(pa + DFF) = acc[0][0][1][0]; *(f32x4*)(pa + DFF + 4) = acc[0][0][1][1];
;                 *(f32x4*)pv = acc[0][1][0][0]; *(f32x4*)(pv + 4) = acc[0][1][0][1]; *(f32x4*)(pv + DFF) = acc[0][1][1][0]; *(f32x4*)(pv + DFF + 4) = acc[0][1][1][1]; }
;             if (fr == 15) { float* pa = HA + ((size_t)kb * 4 + 2) * DFF + jc;
;                 store_wt(pa, __builtin_bit_cast(u32x4, acc[1][0][2][0])); store_wt(pa + 4, __builtin_bit_cast(u32x4, acc[1][0][2][1])); store_wt(pa + DFF, __builtin_bit_cast(u32x4, acc[1][0][3][0])); store_wt(pa + DFF + 4, __builtin_bit_cast(u32x4, acc[1][0][3][1])); } }
.LBB0_1259:
	s_mov_b32 s100, 0xbfb8aa3b
	v_mbcnt_lo_u32_b32 v130, -1, 0
	v_mbcnt_hi_u32_b32 v130, -1, v130
	s_lshl_b32 s27, s11, 8
	v_and_b32_e32 v172, 15, v130
	v_ashrrev_i32_e32 v130, 1, v130
	s_ashr_i32 s25, s10, 4
	v_and_b32_e32 v132, -8, v130
	s_or_b32 s27, s27, s83
	v_add_u32_e32 v130, s27, v132
	s_mul_hi_i32 s27, s25, 0xb000
	s_mul_i32 s25, s25, 0xb000
	s_add_u32 s34, s61, s25
	s_addc_u32 s35, s63, s27
	v_ashrrev_i32_e32 v131, 31, v130
	v_lshl_add_u64 v[130:131], v[130:131], 2, s[34:35]
	global_load_dwordx4 v[142:145], v[130:131], off offset:16
	global_load_dwordx4 v[150:153], v[130:131], off
	global_load_dwordx4 v[134:137], v[130:131], off offset:528
	global_load_dwordx4 v[138:141], v[130:131], off offset:512
	s_lshl_b32 s25, s92, 10
	v_lshl_or_b32 v0, v172, 3, s91
	s_add_i32 s25, s25, 0
	v_lshl_add_u32 v130, v0, 2, s25
	v_add_u32_e32 v130, 0x20400, v130
	ds_read_b128 v[154:157], v130
	ds_read_b128 v[146:149], v130 offset:16
	s_lshl_b32 s11, s11, 7
	s_or_b32 s11, s11, s83
	v_add_u32_e32 v170, s11, v132
	s_lshl_b32 s11, s10, 1
	s_waitcnt lgkmcnt(0)
	v_mov_b32_e32 v130, v149
	s_add_i32 s11, s11, s55
	v_cmp_lt_i32_e32 vcc, 14, v172
	v_ashrrev_i32_e32 v171, 31, v170
	s_waitcnt vmcnt(0)
	v_pk_fma_f32 v[8:9], v[8:9], v[148:149], v[144:145] op_sel_hi:[1,0,1]
	v_pk_fma_f32 v[44:45], v[44:45], v[148:149], v[152:153] op_sel_hi:[1,0,1]
	v_pk_fma_f32 v[42:43], v[42:43], v[148:149], v[150:151] op_sel_hi:[1,0,1]
	v_pk_fma_f32 v[6:7], v[6:7], v[148:149], v[142:143] op_sel_hi:[1,0,1]
	v_pk_fma_f32 v[40:41], v[40:41], v[130:131], v[152:153] op_sel_hi:[1,0,1]
	v_pk_fma_f32 v[38:39], v[38:39], v[130:131], v[150:151] op_sel_hi:[1,0,1]
	v_pk_fma_f32 v[4:5], v[4:5], v[130:131], v[144:145] op_sel_hi:[1,0,1]
	v_pk_fma_f32 v[2:3], v[2:3], v[130:131], v[142:143] op_sel_hi:[1,0,1]
	s_and_saveexec_b64 s[34:35], vcc
	s_xor_b64 s[34:35], exec, s[34:35]
	s_cbranch_execz .LBB0_1261
	s_mul_i32 s27, s11, 0x16000
	s_mul_hi_i32 s25, s11, 0x16000
	s_add_u32 s36, s70, s27
	s_addc_u32 s37, s71, s25
	v_lshl_add_u64 v[130:131], v[170:171], 2, s[36:37]
	s_mov_b64 s[36:37], 0xb000
	v_lshl_add_u64 v[132:133], v[130:131], 0, s[36:37]
	global_store_dwordx4 v[132:133], v[42:45], off sc1
	s_nop 2
	s_mov_b64 s[36:37], 0xb010
	v_lshl_add_u64 v[132:133], v[130:131], 0, s[36:37]
	global_store_dwordx4 v[132:133], v[6:9], off sc1
	s_nop 2
	s_mov_b64 s[36:37], 0x10800
	v_lshl_add_u64 v[132:133], v[130:131], 0, s[36:37]
	global_store_dwordx4 v[132:133], v[38:41], off sc1
	s_nop 2
	s_mov_b64 s[36:37], 0x10810
	v_lshl_add_u64 v[130:131], v[130:131], 0, s[36:37]
	global_store_dwordx4 v[130:131], v[2:5], off sc1
	s_nop 2

; __device__ __forceinline__ void store_wt(void* p, const u32x4 v) { asm volatile("global_store_dwordx4 %0, %1, off sc1\n\ts_nop 2" :: "v"(p), "v"(v) : "memory"); }
; template <int CTRL> __device__ __forceinline__ float dpp_z(float v) { return __int_as_float(__builtin_amdgcn_update_dpp(0, __float_as_int(v), CTRL, 0xf, 0xf, false)); }
;     __device__ __forceinline__ void operator()(f32x4 (&acc)[2][2][4][2], const pg8::Unit& u, int ui, int wr, int wc, int fr, int fq) const {
;     ...
;         {   const int kb = u.pm * 2 + wr;
;             if (fr == 0) { float* pa = HA + ((size_t)kb * 4) * DFF + jc; float* pv = HV + ((size_t)kb * 2) * DFF + jc;
;                 *(f32x4*)pa = acc[0][0][0][0]; *(f32x4*)(pa + 4) = acc[0][0][0][1]; *(f32x4*)(pa + DFF) = acc[0][0][1][0]; *(f32x4*)(pa + DFF + 4) = acc[0][0][1][1];
;                 *(f32x4*)pv = acc[0][1][0][0]; *(f32x4*)(pv + 4) = acc[0][1][0][1]; *(f32x4*)(pv + DFF) = acc[0][1][1][0]; *(f32x4*)(pv + DFF + 4) = acc[0][1][1][1]; }
;             if (fr == 15) { float* pa = HA + ((size_t)kb * 4 + 2) * DFF + jc;
;                 store_wt(pa, __builtin_bit_cast(u32x4, acc[1][0][2][0])); store_wt(pa + 4, __builtin_bit_cast(u32x4, acc[1][0][2][1])); store_wt(pa + DFF, __builtin_bit_cast(u32x4, acc[1][0][3][0])); store_wt(pa + DFF + 4, __builtin_bit_cast(u32x4, acc[1][0][3][1])); } }
; #pragma unroll
;         for (int n = 0; n < 2; ++n) {
;             const f32x4 cbv = *(const f32x4*)(cb + jc + n * 4), w0 = *(const f32x4*)(cw + jc + n * 4), w1 = *(const f32x4*)(cw + DFF + jc + n * 4), w2 = *(const f32x4*)(cw + 2 * DFF + jc + n * 4);
;             f32x4 p2, p1;
;             { const f32x4 x6 = acc[1][0][2][n], x7 = acc[1][0][3][n];
;               p2 = (f32x4){dpp_z<0x111>(x6.x), dpp_z<0x111>(x6.y), dpp_z<0x111>(x6.z), dpp_z<0x111>(x6.w)};
;               p1 = (f32x4){dpp_z<0x111>(x7.x), dpp_z<0x111>(x7.y), dpp_z<0x111>(x7.z), dpp_z<0x111>(x7.w)}; }
; #pragma unroll
;             for (int j = 0; j < 8; ++j) { const f32x4 x = acc[j >> 2][0][j & 3][n];
.LBB0_1265:
	s_or_b64 exec, exec, s[34:35]
	v_mov_b32_e32 v194, v148
	v_mov_b32_e32 v195, v148
	v_pk_fma_f32 v[116:117], v[94:95], v[156:157], v[138:139] op_sel_hi:[1,0,1]
	v_pk_fma_f32 v[94:95], v[108:109], v[156:157], v[144:145] op_sel_hi:[1,0,1]
	v_pk_fma_f32 v[108:109], v[90:91], v[156:157], v[134:135] op_sel_hi:[1,0,1]
	v_mov_b32_e32 v90, v157
	v_mov_b32_e32 v196, v149
	v_mov_b32_e32 v197, v149
	v_pk_fma_f32 v[184:185], v[112:113], v[156:157], v[152:153] op_sel_hi:[1,0,1]
	v_pk_fma_f32 v[186:187], v[110:111], v[156:157], v[150:151] op_sel_hi:[1,0,1]
	v_pk_fma_f32 v[114:115], v[96:97], v[156:157], v[140:141] op_sel_hi:[1,0,1]
	v_pk_fma_f32 v[96:97], v[106:107], v[156:157], v[142:143] op_sel_hi:[1,0,1]
	v_pk_fma_f32 v[106:107], v[92:93], v[156:157], v[136:137] op_sel_hi:[1,0,1]
	v_pk_fma_f32 v[190:191], v[86:87], v[90:91], v[138:139] op_sel_hi:[1,0,1]
	v_pk_fma_f32 v[86:87], v[100:101], v[90:91], v[144:145] op_sel_hi:[1,0,1]
	v_pk_fma_f32 v[100:101], v[82:83], v[90:91], v[134:135] op_sel_hi:[1,0,1]
	v_pk_fma_f32 v[156:157], v[80:81], v[146:147], v[152:153] op_sel_hi:[1,0,1]
	v_pk_fma_f32 v[80:81], v[76:77], v[146:147], v[144:145] op_sel_hi:[1,0,1]
	v_pk_fma_f32 v[82:83], v[50:51], v[146:147], v[134:135] op_sel:[0,1,0]
	v_mov_b32_e32 v50, v148
	v_mov_b32_e32 v51, v148
	v_pk_fma_f32 v[76:77], v[18:19], v[194:195], v[134:135]
	v_lshlrev_b64 v[18:19], 2, v[170:171]
	v_pk_fma_f32 v[176:177], v[104:105], v[90:91], v[152:153] op_sel_hi:[1,0,1]
	v_pk_fma_f32 v[154:155], v[78:79], v[146:147], v[150:151] op_sel_hi:[1,0,1]
	v_pk_fma_f32 v[180:181], v[62:63], v[146:147], v[138:139] op_sel_hi:[1,0,1]
	v_pk_fma_f32 v[78:79], v[74:75], v[146:147], v[142:143] op_sel_hi:[1,0,1]
	v_pk_fma_f32 v[152:153], v[72:73], v[146:147], v[152:153] op_sel:[0,1,0]
	v_pk_fma_f32 v[172:173], v[54:55], v[146:147], v[138:139] op_sel:[0,1,0]
	v_pk_fma_f32 v[72:73], v[68:69], v[146:147], v[144:145] op_sel:[0,1,0]
	v_pk_fma_f32 v[144:145], v[22:23], v[194:195], v[138:139]
	v_pk_fma_f32 v[74:75], v[20:21], v[50:51], v[136:137]
	v_mov_b32_e32 v148, v149
	v_pk_fma_f32 v[138:139], v[14:15], v[196:197], v[138:139]
	v_lshl_add_u64 v[14:15], s[16:17], 0, v[18:19]
	v_lshl_add_u64 v[20:21], s[14:15], 0, v[18:19]
	v_pk_fma_f32 v[178:179], v[102:103], v[90:91], v[150:151] op_sel_hi:[1,0,1]
	v_pk_fma_f32 v[188:189], v[88:89], v[90:91], v[140:141] op_sel_hi:[1,0,1]
	v_pk_fma_f32 v[88:89], v[98:99], v[90:91], v[142:143] op_sel_hi:[1,0,1]
	v_pk_fma_f32 v[98:99], v[84:85], v[90:91], v[136:137] op_sel_hi:[1,0,1]
	v_pk_fma_f32 v[182:183], v[64:65], v[146:147], v[140:141] op_sel_hi:[1,0,1]
	v_pk_fma_f32 v[150:151], v[70:71], v[146:147], v[150:151] op_sel:[0,1,0]
	v_pk_fma_f32 v[174:175], v[56:57], v[146:147], v[140:141] op_sel:[0,1,0]
	v_pk_fma_f32 v[70:71], v[66:67], v[146:147], v[142:143] op_sel:[0,1,0]
	v_pk_fma_f32 v[84:85], v[52:53], v[146:147], v[136:137] op_sel:[0,1,0]
	v_pk_fma_f32 v[142:143], v[24:25], v[50:51], v[140:141]
	v_pk_fma_f32 v[140:141], v[16:17], v[148:149], v[140:141]
	v_pk_fma_f32 v[66:67], v[12:13], v[148:149], v[136:137]
	v_pk_fma_f32 v[68:69], v[10:11], v[196:197], v[134:135]
	global_load_dwordx4 v[10:13], v[14:15], off offset:16
	global_load_dwordx4 v[50:53], v[14:15], off
	s_nop 0
	global_load_dwordx4 v[14:17], v[20:21], off offset:16
	global_load_dwordx4 v[54:57], v[20:21], off
	v_lshl_add_u64 v[20:21], s[20:21], 0, v[18:19]
	v_pk_fma_f32 v[90:91], v[58:59], v[146:147], v[134:135] op_sel_hi:[1,0,1]
	global_load_dwordx4 v[22:25], v[20:21], off offset:16
	global_load_dwordx4 v[62:65], v[20:21], off
	v_lshl_add_u64 v[58:59], s[22:23], 0, v[18:19]
	v_pk_fma_f32 v[92:93], v[60:61], v[146:147], v[136:137] op_sel_hi:[1,0,1]
	global_load_dwordx4 v[18:21], v[58:59], off offset:16
	s_nop 0
	global_load_dwordx4 v[58:61], v[58:59], off
	v_mov_b32_e32 v102, 0
	v_mov_b32_e32 v103, 0
	v_mov_b32_e32 v104, 0
	v_mov_b32_e32 v105, 0
	v_mov_b32_dpp v102, v42 row_shr:1 row_mask:0xf bank_mask:0xf
	v_mov_b32_dpp v103, v43 row_shr:1 row_mask:0xf bank_mask:0xf
	v_mov_b32_dpp v104, v44 row_shr:1 row_mask:0xf bank_mask:0xf
	v_mov_b32_dpp v105, v45 row_shr:1 row_mask:0xf bank_mask:0xf
	v_mov_b32_e32 v110, 0
	v_mov_b32_e32 v111, 0
	v_mov_b32_e32 v112, 0
	v_mov_b32_e32 v113, 0
	v_mov_b32_dpp v110, v38 row_shr:1 row_mask:0xf bank_mask:0xf
	v_mov_b32_dpp v111, v39 row_shr:1 row_mask:0xf bank_mask:0xf
	v_mov_b32_dpp v112, v40 row_shr:1 row_mask:0xf bank_mask:0xf
	v_mov_b32_dpp v113, v41 row_shr:1 row_mask:0xf bank_mask:0xf
	s_mul_hi_i32 s11, s10, 0x2c0000
	s_mul_i32 s10, s10, 0x2c0000
	s_add_u32 s10, s67, s10
	s_addc_u32 s11, s68, s11
	s_andn2_b64 vcc, exec, s[6:7]
	s_waitcnt vmcnt(4)
	v_pk_fma_f32 v[104:105], v[56:57], v[104:105], v[52:53]
	v_pk_fma_f32 v[102:103], v[54:55], v[102:103], v[50:51]
	s_waitcnt vmcnt(2)
	v_pk_fma_f32 v[104:105], v[64:65], v[112:113], v[104:105]
	v_pk_fma_f32 v[102:103], v[62:63], v[110:111], v[102:103]
	v_pk_fma_f32 v[112:113], v[56:57], v[112:113], v[52:53]
	s_waitcnt vmcnt(0)
; __device__ __forceinline__ f32x4 silu4(const f32x4 p) { f32x4 r; r.x = siluf(p.x); r.y = siluf(p.y); r.z = siluf(p.z); r.w = siluf(p.w); return r; }
; template <int CTRL> __device__ __forceinline__ float dpp_z(float v) { return __int_as_float(__builtin_amdgcn_update_dpp(0, __float_as_int(v), CTRL, 0xf, 0xf, false)); }
; __device__ __forceinline__ float siluf(float x) { return x * __builtin_amdgcn_rcpf(1.f + __expf(-x)); }
;     __device__ __forceinline__ void operator()(f32x4 (&acc)[2][2][4][2], const pg8::Unit& u, int ui, int wr, int wc, int fr, int fq) const {
;     ...
;         for (int n = 0; n < 2; ++n) {
;             const f32x4 cbv = *(const f32x4*)(cb + jc + n * 4), w0 = *(const f32x4*)(cw + jc + n * 4), w1 = *(const f32x4*)(cw + DFF + jc + n * 4), w2 = *(const f32x4*)(cw + 2 * DFF + jc + n * 4);
;             f32x4 p2, p1;
;             { const f32x4 x6 = acc[1][0][2][n], x7 = acc[1][0][3][n];
;               p2 = (f32x4){dpp_z<0x111>(x6.x), dpp_z<0x111>(x6.y), dpp_z<0x111>(x6.z), dpp_z<0x111>(x6.w)};
;               p1 = (f32x4){dpp_z<0x111>(x7.x), dpp_z<0x111>(x7.y), dpp_z<0x111>(x7.z), dpp_z<0x111>(x7.w)}; }
; #pragma unroll
;             for (int j = 0; j < 8; ++j) { const f32x4 x = acc[j >> 2][0][j & 3][n];
;                 const f32x4 cv = cbv + w0 * p2 + w1 * p1 + w2 * x;
;                 acc[j >> 2][1][j & 3][n] = silu4(cv) * acc[j >> 2][1][j & 3][n];
;                 p2 = p1; p1 = x; }
	v_pk_fma_f32 v[104:105], v[128:129], v[60:61], v[104:105]
	v_pk_fma_f32 v[102:103], v[126:127], v[58:59], v[102:103]
	v_pk_mul_f32 v[136:137], v[104:105], s[100:101] op_sel_hi:[1,0]
	v_pk_mul_f32 v[134:135], v[102:103], s[100:101] op_sel_hi:[1,0]
	v_exp_f32_e32 v134, v134
	v_exp_f32_e32 v135, v135
	v_exp_f32_e32 v136, v136
	v_exp_f32_e32 v137, v137
	v_pk_add_f32 v[134:135], v[134:135], 1.0 op_sel_hi:[1,0]
	v_pk_add_f32 v[136:137], v[136:137], 1.0 op_sel_hi:[1,0]
	v_rcp_f32_e32 v134, v134
	v_rcp_f32_e32 v135, v135
	v_rcp_f32_e32 v136, v136
	v_rcp_f32_e32 v137, v137
	v_pk_fma_f32 v[110:111], v[54:55], v[110:111], v[50:51]
	v_pk_fma_f32 v[112:113], v[128:129], v[64:65], v[112:113]
	v_pk_fma_f32 v[110:111], v[126:127], v[62:63], v[110:111]
	v_pk_mul_f32 v[104:105], v[104:105], v[136:137]
	v_pk_mul_f32 v[134:135], v[102:103], v[134:135]
	v_pk_fma_f32 v[112:113], v[120:121], v[60:61], v[112:113]
	v_pk_fma_f32 v[110:111], v[118:119], v[58:59], v[110:111]
	v_pk_mul_f32 v[102:103], v[132:133], v[104:105]
	v_pk_mul_f32 v[104:105], v[130:131], v[134:135]
	v_pk_mul_f32 v[130:131], v[110:111], s[100:101] op_sel_hi:[1,0]
	v_pk_mul_f32 v[132:133], v[112:113], s[100:101] op_sel_hi:[1,0]
	v_exp_f32_e32 v130, v130
	v_exp_f32_e32 v131, v131
	v_exp_f32_e32 v132, v132
	v_exp_f32_e32 v133, v133
	v_pk_add_f32 v[130:131], v[130:131], 1.0 op_sel_hi:[1,0]
	v_pk_add_f32 v[132:133], v[132:133], 1.0 op_sel_hi:[1,0]
	v_rcp_f32_e32 v130, v130
	v_rcp_f32_e32 v131, v131
	v_rcp_f32_e32 v132, v132
	v_rcp_f32_e32 v133, v133
	v_pk_mul_f32 v[130:131], v[110:111], v[130:131]
	v_pk_mul_f32 v[112:113], v[112:113], v[132:133]
	s_nop 0
	v_pk_mul_f32 v[110:111], v[124:125], v[112:113]
	v_pk_mul_f32 v[112:113], v[122:123], v[130:131]
	v_pk_fma_f32 v[122:123], v[128:129], v[56:57], v[52:53]
	v_pk_fma_f32 v[124:125], v[126:127], v[54:55], v[50:51]
	v_pk_fma_f32 v[122:123], v[120:121], v[64:65], v[122:123]
	v_pk_fma_f32 v[124:125], v[118:119], v[62:63], v[124:125]
	v_pk_fma_f32 v[122:123], v[184:185], v[60:61], v[122:123]
	v_pk_fma_f32 v[124:125], v[186:187], v[58:59], v[124:125]
	v_pk_mul_f32 v[128:129], v[122:123], s[100:101] op_sel_hi:[1,0]
	v_pk_mul_f32 v[126:127], v[124:125], s[100:101] op_sel_hi:[1,0]
	v_exp_f32_e32 v126, v126
	v_exp_f32_e32 v127, v127
	v_exp_f32_e32 v128, v128
	v_exp_f32_e32 v129, v129
	v_pk_add_f32 v[126:127], v[126:127], 1.0 op_sel_hi:[1,0]
	v_pk_add_f32 v[128:129], v[128:129], 1.0 op_sel_hi:[1,0]
	v_rcp_f32_e32 v126, v126
	v_rcp_f32_e32 v127, v127
	v_rcp_f32_e32 v128, v128
	v_rcp_f32_e32 v129, v129
	v_pk_fma_f32 v[120:121], v[120:121], v[56:57], v[52:53]
	v_pk_fma_f32 v[118:119], v[118:119], v[54:55], v[50:51]
	v_pk_fma_f32 v[120:121], v[184:185], v[64:65], v[120:121]
	v_pk_fma_f32 v[118:119], v[186:187], v[62:63], v[118:119]
	v_pk_mul_f32 v[122:123], v[122:123], v[128:129]
	v_pk_mul_f32 v[124:125], v[124:125], v[126:127]
	v_pk_fma_f32 v[120:121], v[176:177], v[60:61], v[120:121]
	v_pk_fma_f32 v[118:119], v[178:179], v[58:59], v[118:119]
	v_pk_mul_f32 v[114:115], v[114:115], v[122:123]
	v_pk_mul_f32 v[116:117], v[116:117], v[124:125]
	v_pk_mul_f32 v[122:123], v[118:119], s[100:101] op_sel_hi:[1,0]
	v_pk_mul_f32 v[124:125], v[120:121], s[100:101] op_sel_hi:[1,0]
	v_exp_f32_e32 v122, v122
	v_exp_f32_e32 v123, v123
	v_exp_f32_e32 v124, v124
	v_exp_f32_e32 v125, v125
	v_pk_add_f32 v[122:123], v[122:123], 1.0 op_sel_hi:[1,0]
	v_pk_add_f32 v[124:125], v[124:125], 1.0 op_sel_hi:[1,0]
	v_rcp_f32_e32 v122, v122
	v_rcp_f32_e32 v123, v123
	v_rcp_f32_e32 v124, v124
	v_rcp_f32_e32 v125, v125
	v_pk_mul_f32 v[122:123], v[118:119], v[122:123]
	v_pk_mul_f32 v[120:121], v[120:121], v[124:125]
	s_nop 0
	v_pk_mul_f32 v[118:119], v[188:189], v[120:121]
	v_pk_mul_f32 v[120:121], v[190:191], v[122:123]
	v_pk_fma_f32 v[122:123], v[186:187], v[54:55], v[50:51]
	v_pk_fma_f32 v[124:125], v[184:185], v[56:57], v[52:53]
	v_pk_fma_f32 v[122:123], v[178:179], v[62:63], v[122:123]
	v_pk_fma_f32 v[124:125], v[176:177], v[64:65], v[124:125]
	v_pk_fma_f32 v[122:123], v[154:155], v[58:59], v[122:123]
	v_pk_fma_f32 v[124:125], v[156:157], v[60:61], v[124:125]
	v_pk_mul_f32 v[126:127], v[122:123], s[100:101] op_sel_hi:[1,0]
	v_pk_mul_f32 v[128:129], v[124:125], s[100:101] op_sel_hi:[1,0]
	v_exp_f32_e32 v126, v126
	v_exp_f32_e32 v127, v127
	v_exp_f32_e32 v128, v128
	v_exp_f32_e32 v129, v129
	v_pk_add_f32 v[126:127], v[126:127], 1.0 op_sel_hi:[1,0]
	v_pk_add_f32 v[128:129], v[128:129], 1.0 op_sel_hi:[1,0]
	v_rcp_f32_e32 v126, v126
	v_rcp_f32_e32 v127, v127
	v_rcp_f32_e32 v128, v128
	v_rcp_f32_e32 v129, v129
	v_pk_mul_f32 v[126:127], v[122:123], v[126:127]
	v_pk_mul_f32 v[124:125], v[124:125], v[128:129]
	s_nop 0
	v_pk_mul_f32 v[122:123], v[182:183], v[124:125]
	v_pk_mul_f32 v[124:125], v[180:181], v[126:127]
	v_pk_fma_f32 v[126:127], v[176:177], v[56:57], v[52:53]
	v_pk_fma_f32 v[128:129], v[178:179], v[54:55], v[50:51]
	v_pk_fma_f32 v[126:127], v[156:157], v[64:65], v[126:127]
	v_pk_fma_f32 v[128:129], v[154:155], v[62:63], v[128:129]
	v_pk_fma_f32 v[126:127], v[152:153], v[60:61], v[126:127]
	v_pk_fma_f32 v[128:129], v[150:151], v[58:59], v[128:129]
	v_pk_mul_f32 v[132:133], v[126:127], s[100:101] op_sel_hi:[1,0]
	v_pk_mul_f32 v[130:131], v[128:129], s[100:101] op_sel_hi:[1,0]
	v_exp_f32_e32 v130, v130
	v_exp_f32_e32 v131, v131
	v_exp_f32_e32 v132, v132
	v_exp_f32_e32 v133, v133
	v_pk_add_f32 v[130:131], v[130:131], 1.0 op_sel_hi:[1,0]
	v_pk_add_f32 v[132:133], v[132:133], 1.0 op_sel_hi:[1,0]
	v_rcp_f32_e32 v130, v130
	v_rcp_f32_e32 v131, v131
	v_rcp_f32_e32 v132, v132
	v_rcp_f32_e32 v133, v133
	v_pk_mul_f32 v[128:129], v[128:129], v[130:131]
	v_pk_fma_f32 v[130:131], v[156:157], v[56:57], v[52:53]
; __device__ __forceinline__ f32x4 silu4(const f32x4 p) { f32x4 r; r.x = siluf(p.x); r.y = siluf(p.y); r.z = siluf(p.z); r.w = siluf(p.w); return r; }
; template <int CTRL> __device__ __forceinline__ float dpp_z(float v) { return __int_as_float(__builtin_amdgcn_update_dpp(0, __float_as_int(v), CTRL, 0xf, 0xf, false)); }
; __device__ __forceinline__ float siluf(float x) { return x * __builtin_amdgcn_rcpf(1.f + __expf(-x)); }
;     __device__ __forceinline__ void operator()(f32x4 (&acc)[2][2][4][2], const pg8::Unit& u, int ui, int wr, int wc, int fr, int fq) const {
;     ...
;         for (int n = 0; n < 2; ++n) {
;             const f32x4 cbv = *(const f32x4*)(cb + jc + n * 4), w0 = *(const f32x4*)(cw + jc + n * 4), w1 = *(const f32x4*)(cw + DFF + jc + n * 4), w2 = *(const f32x4*)(cw + 2 * DFF + jc + n * 4);
;             f32x4 p2, p1;
;             { const f32x4 x6 = acc[1][0][2][n], x7 = acc[1][0][3][n];
;               p2 = (f32x4){dpp_z<0x111>(x6.x), dpp_z<0x111>(x6.y), dpp_z<0x111>(x6.z), dpp_z<0x111>(x6.w)};
;               p1 = (f32x4){dpp_z<0x111>(x7.x), dpp_z<0x111>(x7.y), dpp_z<0x111>(x7.z), dpp_z<0x111>(x7.w)}; }
; #pragma unroll
;             for (int j = 0; j < 8; ++j) { const f32x4 x = acc[j >> 2][0][j & 3][n];
;                 const f32x4 cv = cbv + w0 * p2 + w1 * p1 + w2 * x;
;                 acc[j >> 2][1][j & 3][n] = silu4(cv) * acc[j >> 2][1][j & 3][n];
;                 p2 = p1; p1 = x; }
	v_pk_mul_f32 v[126:127], v[126:127], v[132:133]
	v_pk_fma_f32 v[132:133], v[154:155], v[54:55], v[50:51]
	v_pk_fma_f32 v[130:131], v[152:153], v[64:65], v[130:131]
	v_pk_fma_f32 v[132:133], v[150:151], v[62:63], v[132:133]
	v_pk_fma_f32 v[52:53], v[152:153], v[56:57], v[52:53]
	v_pk_fma_f32 v[50:51], v[150:151], v[54:55], v[50:51]
	v_pk_fma_f32 v[130:131], v[44:45], v[60:61], v[130:131]
	v_pk_fma_f32 v[132:133], v[42:43], v[58:59], v[132:133]
	v_pk_fma_f32 v[44:45], v[44:45], v[64:65], v[52:53]
	v_pk_fma_f32 v[42:43], v[42:43], v[62:63], v[50:51]
	v_pk_fma_f32 v[40:41], v[40:41], v[60:61], v[44:45]
	v_pk_fma_f32 v[38:39], v[38:39], v[58:59], v[42:43]
	v_pk_mul_f32 v[44:45], v[40:41], s[100:101] op_sel_hi:[1,0]
	v_pk_mul_f32 v[42:43], v[38:39], s[100:101] op_sel_hi:[1,0]
	v_exp_f32_e32 v42, v42
	v_exp_f32_e32 v43, v43
	v_exp_f32_e32 v44, v44
	v_exp_f32_e32 v45, v45
	v_pk_add_f32 v[42:43], v[42:43], 1.0 op_sel_hi:[1,0]
	v_pk_add_f32 v[44:45], v[44:45], 1.0 op_sel_hi:[1,0]
	v_rcp_f32_e32 v42, v42
	v_rcp_f32_e32 v43, v43
	v_rcp_f32_e32 v44, v44
	v_rcp_f32_e32 v45, v45
	v_mov_b32_e32 v50, 0
	v_pk_mul_f32 v[42:43], v[38:39], v[42:43]
	v_mov_b32_e32 v51, 0
	v_pk_mul_f32 v[40:41], v[40:41], v[44:45]
	v_mov_b32_e32 v44, 0
	v_pk_mul_f32 v[38:39], v[140:141], v[40:41]
	v_pk_mul_f32 v[40:41], v[138:139], v[42:43]
	v_mov_b32_e32 v42, 0
	v_mov_b32_e32 v43, 0
	v_mov_b32_e32 v45, 0
	v_mov_b32_dpp v42, v6 row_shr:1 row_mask:0xf bank_mask:0xf
	v_mov_b32_dpp v43, v7 row_shr:1 row_mask:0xf bank_mask:0xf
	v_mov_b32_dpp v44, v8 row_shr:1 row_mask:0xf bank_mask:0xf
	v_mov_b32_dpp v45, v9 row_shr:1 row_mask:0xf bank_mask:0xf
	v_mov_b32_e32 v52, 0
	v_mov_b32_e32 v53, 0
	v_mov_b32_dpp v50, v2 row_shr:1 row_mask:0xf bank_mask:0xf
	v_mov_b32_dpp v51, v3 row_shr:1 row_mask:0xf bank_mask:0xf
	v_mov_b32_dpp v52, v4 row_shr:1 row_mask:0xf bank_mask:0xf
	v_mov_b32_dpp v53, v5 row_shr:1 row_mask:0xf bank_mask:0xf
	v_pk_fma_f32 v[44:45], v[16:17], v[44:45], v[12:13]
	v_pk_fma_f32 v[42:43], v[14:15], v[42:43], v[10:11]
	v_pk_fma_f32 v[44:45], v[24:25], v[52:53], v[44:45]
	v_pk_fma_f32 v[42:43], v[22:23], v[50:51], v[42:43]
	v_pk_fma_f32 v[44:45], v[32:33], v[20:21], v[44:45]
	v_pk_fma_f32 v[42:43], v[30:31], v[18:19], v[42:43]
	v_pk_mul_f32 v[56:57], v[44:45], s[100:101] op_sel_hi:[1,0]
	v_pk_mul_f32 v[54:55], v[42:43], s[100:101] op_sel_hi:[1,0]
	v_exp_f32_e32 v54, v54
	v_exp_f32_e32 v55, v55
	v_exp_f32_e32 v56, v56
	v_exp_f32_e32 v57, v57
	v_pk_add_f32 v[54:55], v[54:55], 1.0 op_sel_hi:[1,0]
	v_pk_add_f32 v[56:57], v[56:57], 1.0 op_sel_hi:[1,0]
	v_rcp_f32_e32 v54, v54
	v_rcp_f32_e32 v55, v55
	v_rcp_f32_e32 v56, v56
	v_rcp_f32_e32 v57, v57
	v_mul_f32_e32 v134, 0xbfb8aa3b, v132
	v_pk_mul_f32 v[54:55], v[42:43], v[54:55]
	v_mul_f32_e32 v135, 0xbfb8aa3b, v133
	v_pk_mul_f32 v[44:45], v[44:45], v[56:57]
	v_mul_f32_e32 v136, 0xbfb8aa3b, v130
	v_pk_mul_f32 v[42:43], v[48:49], v[44:45]
	v_pk_mul_f32 v[44:45], v[46:47], v[54:55]
	v_pk_fma_f32 v[46:47], v[16:17], v[52:53], v[12:13]
	v_pk_fma_f32 v[48:49], v[14:15], v[50:51], v[10:11]
	v_pk_fma_f32 v[46:47], v[32:33], v[24:25], v[46:47]
	v_pk_fma_f32 v[48:49], v[30:31], v[22:23], v[48:49]
	v_pk_fma_f32 v[46:47], v[28:29], v[20:21], v[46:47]
	v_pk_fma_f32 v[48:49], v[26:27], v[18:19], v[48:49]
	v_pk_mul_f32 v[52:53], v[46:47], s[100:101] op_sel_hi:[1,0]
	v_pk_mul_f32 v[50:51], v[48:49], s[100:101] op_sel_hi:[1,0]
	v_exp_f32_e32 v50, v50
	v_exp_f32_e32 v51, v51
	v_exp_f32_e32 v52, v52
	v_exp_f32_e32 v53, v53
	v_pk_add_f32 v[50:51], v[50:51], 1.0 op_sel_hi:[1,0]
	v_pk_add_f32 v[52:53], v[52:53], 1.0 op_sel_hi:[1,0]
	v_rcp_f32_e32 v50, v50
	v_rcp_f32_e32 v51, v51
	v_rcp_f32_e32 v52, v52
	v_rcp_f32_e32 v53, v53
	v_pk_fma_f32 v[32:33], v[32:33], v[16:17], v[12:13]
	v_pk_fma_f32 v[30:31], v[30:31], v[14:15], v[10:11]
	v_pk_fma_f32 v[32:33], v[28:29], v[24:25], v[32:33]
	v_pk_fma_f32 v[30:31], v[26:27], v[22:23], v[30:31]
	v_pk_mul_f32 v[46:47], v[46:47], v[52:53]
	v_pk_mul_f32 v[48:49], v[48:49], v[50:51]
	v_pk_fma_f32 v[32:33], v[94:95], v[20:21], v[32:33]
	v_pk_fma_f32 v[30:31], v[96:97], v[18:19], v[30:31]
	v_pk_mul_f32 v[36:37], v[36:37], v[46:47]
	v_pk_mul_f32 v[34:35], v[34:35], v[48:49]
	v_pk_mul_f32 v[46:47], v[30:31], s[100:101] op_sel_hi:[1,0]
	v_pk_mul_f32 v[48:49], v[32:33], s[100:101] op_sel_hi:[1,0]
	v_exp_f32_e32 v46, v46
	v_exp_f32_e32 v47, v47
	v_exp_f32_e32 v48, v48
	v_exp_f32_e32 v49, v49
	v_pk_add_f32 v[46:47], v[46:47], 1.0 op_sel_hi:[1,0]
	v_pk_add_f32 v[48:49], v[48:49], 1.0 op_sel_hi:[1,0]
	v_rcp_f32_e32 v46, v46
	v_rcp_f32_e32 v47, v47
	v_rcp_f32_e32 v48, v48
	v_rcp_f32_e32 v49, v49
	v_pk_fma_f32 v[28:29], v[28:29], v[16:17], v[12:13]
	v_pk_fma_f32 v[26:27], v[26:27], v[14:15], v[10:11]
	v_pk_fma_f32 v[28:29], v[94:95], v[24:25], v[28:29]
	v_pk_fma_f32 v[26:27], v[96:97], v[22:23], v[26:27]
	v_pk_mul_f32 v[32:33], v[32:33], v[48:49]
	v_pk_mul_f32 v[46:47], v[30:31], v[46:47]
	v_pk_fma_f32 v[28:29], v[86:87], v[20:21], v[28:29]
	v_pk_fma_f32 v[26:27], v[88:89], v[18:19], v[26:27]
	v_pk_mul_f32 v[30:31], v[106:107], v[32:33]
	v_pk_mul_f32 v[32:33], v[108:109], v[46:47]
	v_pk_mul_f32 v[46:47], v[26:27], s[100:101] op_sel_hi:[1,0]
	v_pk_mul_f32 v[48:49], v[28:29], s[100:101] op_sel_hi:[1,0]
	v_exp_f32_e32 v46, v46
	v_exp_f32_e32 v47, v47
	v_exp_f32_e32 v48, v48
	v_exp_f32_e32 v49, v49
	v_pk_add_f32 v[46:47], v[46:47], 1.0 op_sel_hi:[1,0]
	v_pk_add_f32 v[48:49], v[48:49], 1.0 op_sel_hi:[1,0]
	v_rcp_f32_e32 v46, v46
	v_rcp_f32_e32 v47, v47
	v_rcp_f32_e32 v48, v48
	v_rcp_f32_e32 v49, v49
	v_mul_f32_e32 v137, 0xbfb8aa3b, v131
	v_pk_mul_f32 v[46:47], v[26:27], v[46:47]
	v_exp_f32_e32 v134, v134
	v_pk_mul_f32 v[28:29], v[28:29], v[48:49]
; __device__ __forceinline__ u32x4 pack8(const f32x4 a, const f32x4 b) { u32x4 w; w.x = cvt_pk_bf16(a.x, a.y); w.y = cvt_pk_bf16(a.z, a.w); w.z = cvt_pk_bf16(b.x, b.y); w.w = cvt_pk_bf16(b.z, b.w); return w; }
; __device__ __forceinline__ f32x4 silu4(const f32x4 p) { f32x4 r; r.x = siluf(p.x); r.y = siluf(p.y); r.z = siluf(p.z); r.w = siluf(p.w); return r; }
; template <int CTRL> __device__ __forceinline__ float dpp_z(float v) { return __int_as_float(__builtin_amdgcn_update_dpp(0, __float_as_int(v), CTRL, 0xf, 0xf, false)); }
; __device__ __forceinline__ float siluf(float x) { return x * __builtin_amdgcn_rcpf(1.f + __expf(-x)); }
;     __device__ __forceinline__ void operator()(f32x4 (&acc)[2][2][4][2], const pg8::Unit& u, int ui, int wr, int wc, int fr, int fq) const {
;     ...
;         for (int n = 0; n < 2; ++n) {
;             const f32x4 cbv = *(const f32x4*)(cb + jc + n * 4), w0 = *(const f32x4*)(cw + jc + n * 4), w1 = *(const f32x4*)(cw + DFF + jc + n * 4), w2 = *(const f32x4*)(cw + 2 * DFF + jc + n * 4);
;             f32x4 p2, p1;
;             { const f32x4 x6 = acc[1][0][2][n], x7 = acc[1][0][3][n];
;               p2 = (f32x4){dpp_z<0x111>(x6.x), dpp_z<0x111>(x6.y), dpp_z<0x111>(x6.z), dpp_z<0x111>(x6.w)};
;               p1 = (f32x4){dpp_z<0x111>(x7.x), dpp_z<0x111>(x7.y), dpp_z<0x111>(x7.z), dpp_z<0x111>(x7.w)}; }
; #pragma unroll
;             for (int j = 0; j < 8; ++j) { const f32x4 x = acc[j >> 2][0][j & 3][n];
;                 const f32x4 cv = cbv + w0 * p2 + w1 * p1 + w2 * x;
;                 acc[j >> 2][1][j & 3][n] = silu4(cv) * acc[j >> 2][1][j & 3][n];
;                 p2 = p1; p1 = x; }
;         }
; #pragma unroll
;         for (int j = 0; j < 8; ++j) *(u32x4*)(ACT + (size_t)u.pm * (256 * DFF) + (size_t)(jc >> 6) * (256 * 64) + (lrow + j) * 64 + (jc & 63)) = pack8(acc[j >> 2][1][j & 3][0], acc[j >> 2][1][j & 3][1]);
	v_pk_fma_f32 v[48:49], v[94:95], v[16:17], v[12:13]
	v_pk_mul_f32 v[26:27], v[98:99], v[28:29]
	v_pk_mul_f32 v[28:29], v[100:101], v[46:47]
	v_pk_fma_f32 v[46:47], v[96:97], v[14:15], v[10:11]
	v_pk_fma_f32 v[48:49], v[86:87], v[24:25], v[48:49]
	v_pk_fma_f32 v[46:47], v[88:89], v[22:23], v[46:47]
	v_pk_fma_f32 v[48:49], v[80:81], v[20:21], v[48:49]
	v_pk_fma_f32 v[46:47], v[78:79], v[18:19], v[46:47]
	v_pk_mul_f32 v[52:53], v[48:49], s[100:101] op_sel_hi:[1,0]
	v_pk_mul_f32 v[50:51], v[46:47], s[100:101] op_sel_hi:[1,0]
	v_exp_f32_e32 v50, v50
	v_exp_f32_e32 v51, v51
	v_exp_f32_e32 v52, v52
	v_exp_f32_e32 v53, v53
	v_pk_add_f32 v[50:51], v[50:51], 1.0 op_sel_hi:[1,0]
	v_pk_add_f32 v[52:53], v[52:53], 1.0 op_sel_hi:[1,0]
	v_rcp_f32_e32 v50, v50
	v_rcp_f32_e32 v51, v51
	v_rcp_f32_e32 v52, v52
	v_rcp_f32_e32 v53, v53
	v_exp_f32_e32 v135, v135
	v_pk_mul_f32 v[50:51], v[46:47], v[50:51]
	v_exp_f32_e32 v136, v136
	v_pk_mul_f32 v[48:49], v[48:49], v[52:53]
	v_pk_fma_f32 v[52:53], v[88:89], v[14:15], v[10:11]
	v_pk_mul_f32 v[46:47], v[92:93], v[48:49]
	v_pk_mul_f32 v[48:49], v[90:91], v[50:51]
	v_pk_fma_f32 v[50:51], v[86:87], v[16:17], v[12:13]
	v_pk_fma_f32 v[52:53], v[78:79], v[22:23], v[52:53]
	v_pk_fma_f32 v[50:51], v[80:81], v[24:25], v[50:51]
	v_pk_fma_f32 v[52:53], v[70:71], v[18:19], v[52:53]
	v_pk_fma_f32 v[50:51], v[72:73], v[20:21], v[50:51]
	v_pk_mul_f32 v[54:55], v[52:53], s[100:101] op_sel_hi:[1,0]
	v_pk_mul_f32 v[56:57], v[50:51], s[100:101] op_sel_hi:[1,0]
	v_exp_f32_e32 v56, v56
	v_exp_f32_e32 v57, v57
	v_exp_f32_e32 v54, v54
	v_exp_f32_e32 v55, v55
	v_pk_add_f32 v[56:57], v[56:57], 1.0 op_sel_hi:[1,0]
	v_pk_add_f32 v[54:55], v[54:55], 1.0 op_sel_hi:[1,0]
	v_rcp_f32_e32 v56, v56
	v_rcp_f32_e32 v57, v57
	v_rcp_f32_e32 v54, v54
	v_rcp_f32_e32 v55, v55
	v_exp_f32_e32 v137, v137
	v_pk_mul_f32 v[50:51], v[50:51], v[56:57]
	v_pk_fma_f32 v[56:57], v[78:79], v[14:15], v[10:11]
	v_pk_mul_f32 v[52:53], v[52:53], v[54:55]
	v_pk_fma_f32 v[54:55], v[80:81], v[16:17], v[12:13]
	v_pk_fma_f32 v[56:57], v[70:71], v[22:23], v[56:57]
	v_pk_fma_f32 v[10:11], v[70:71], v[14:15], v[10:11]
	v_pk_fma_f32 v[54:55], v[72:73], v[24:25], v[54:55]
	v_pk_fma_f32 v[56:57], v[6:7], v[18:19], v[56:57]
	v_pk_fma_f32 v[12:13], v[72:73], v[16:17], v[12:13]
	v_pk_fma_f32 v[6:7], v[6:7], v[22:23], v[10:11]
	v_pk_fma_f32 v[54:55], v[8:9], v[20:21], v[54:55]
	v_pk_fma_f32 v[8:9], v[8:9], v[24:25], v[12:13]
	v_pk_fma_f32 v[2:3], v[2:3], v[18:19], v[6:7]
	v_pk_fma_f32 v[4:5], v[4:5], v[20:21], v[8:9]
	v_pk_mul_f32 v[6:7], v[2:3], s[100:101] op_sel_hi:[1,0]
	v_exp_f32_e32 v6, v6
	v_exp_f32_e32 v7, v7
	v_pk_mul_f32 v[8:9], v[4:5], s[100:101] op_sel_hi:[1,0]
	v_exp_f32_e32 v8, v8
	v_exp_f32_e32 v9, v9
	v_pk_add_f32 v[6:7], v[6:7], 1.0 op_sel_hi:[1,0]
	v_rcp_f32_e32 v6, v6
	v_rcp_f32_e32 v7, v7
	v_pk_add_f32 v[8:9], v[8:9], 1.0 op_sel_hi:[1,0]
	v_rcp_f32_e32 v8, v8
	v_rcp_f32_e32 v9, v9
	v_pk_mul_f32 v[2:3], v[2:3], v[6:7]
	v_pk_mul_f32 v[58:59], v[56:57], s[100:101] op_sel_hi:[1,0]
	v_pk_mul_f32 v[60:61], v[54:55], s[100:101] op_sel_hi:[1,0]
	v_pk_mul_f32 v[4:5], v[4:5], v[8:9]
	v_pk_mul_f32 v[8:9], v[68:69], v[2:3]
	v_ashrrev_i32_e32 v2, 6, v170
	v_exp_f32_e32 v58, v58
	v_exp_f32_e32 v59, v59
	v_exp_f32_e32 v60, v60
	v_exp_f32_e32 v61, v61
	v_ashrrev_i32_e32 v3, 31, v2
	v_lshlrev_b64 v[10:11], 15, v[2:3]
	v_and_b32_e32 v12, 0x80, v0
	v_lshlrev_b32_e32 v12, 6, v12
	v_and_b32_e32 v248, 0x78, v0
	v_lshl_or_b32 v12, v248, 2, v12
	v_and_b32_e32 v14, 56, v170
	v_lshl_add_u64 v[10:11], s[10:11], 0, v[10:11]
	v_ashrrev_i32_e32 v13, 31, v12
	v_lshl_add_u64 v[10:11], v[12:13], 1, v[10:11]
	v_and_b32_e32 v248, 32, v14
	v_lshlrev_b32_e32 v248, 5, v248
	v_and_b32_e32 v0, 24, v14
	v_lshl_or_b32 v0, v0, 1, v248
	v_mov_b32_e32 v250, 0x1000
	v_mov_b32_e32 v251, 0
	v_pk_add_f32 v[134:135], v[134:135], 1.0 op_sel_hi:[1,0]
	v_pk_add_f32 v[136:137], v[136:137], 1.0 op_sel_hi:[1,0]
	v_pk_add_f32 v[58:59], v[58:59], 1.0 op_sel_hi:[1,0]
	v_pk_add_f32 v[60:61], v[60:61], 1.0 op_sel_hi:[1,0]
	v_pk_mul_f32 v[6:7], v[66:67], v[4:5]
	v_cvt_pk_bf16_f32 v2, v104, v105
	v_cvt_pk_bf16_f32 v3, v102, v103
	v_cvt_pk_bf16_f32 v4, v44, v45
	v_cvt_pk_bf16_f32 v5, v42, v43
	v_lshl_add_u64 v[10:11], v[10:11], 0, v[0:1]
	v_rcp_f32_e32 v134, v134
	v_rcp_f32_e32 v135, v135
	v_rcp_f32_e32 v136, v136
	v_rcp_f32_e32 v137, v137
	v_rcp_f32_e32 v58, v58
	v_rcp_f32_e32 v59, v59
	v_rcp_f32_e32 v60, v60
	v_rcp_f32_e32 v61, v61
	global_store_dwordx4 v[10:11], v[2:5], off
	v_pk_mul_f32 v[126:127], v[174:175], v[126:127]
	v_pk_mul_f32 v[128:129], v[172:173], v[128:129]
	v_cvt_pk_bf16_f32 v2, v112, v113
	v_cvt_pk_bf16_f32 v3, v110, v111
	v_cvt_pk_bf16_f32 v4, v34, v35
	v_cvt_pk_bf16_f32 v5, v36, v37
	global_store_dwordx4 v[10:11], v[2:5], off offset:2048
	v_pk_mul_f32 v[130:131], v[130:131], v[136:137]
	v_pk_mul_f32 v[132:133], v[132:133], v[134:135]
	v_cvt_pk_bf16_f32 v2, v116, v117
	v_cvt_pk_bf16_f32 v3, v114, v115
	v_cvt_pk_bf16_f32 v4, v32, v33
	v_cvt_pk_bf16_f32 v5, v30, v31
	v_lshl_add_u64 v[10:11], v[10:11], 0, v[250:251]
	global_store_dwordx4 v[10:11], v[2:5], off
	v_pk_mul_f32 v[50:51], v[84:85], v[50:51]
	v_pk_mul_f32 v[52:53], v[82:83], v[52:53]
	v_cvt_pk_bf16_f32 v2, v120, v121
	v_cvt_pk_bf16_f32 v3, v118, v119
	v_cvt_pk_bf16_f32 v4, v28, v29
	v_cvt_pk_bf16_f32 v5, v26, v27
	global_store_dwordx4 v[10:11], v[2:5], off offset:2048
	v_pk_mul_f32 v[54:55], v[54:55], v[60:61]
	v_pk_mul_f32 v[56:57], v[56:57], v[58:59]
	v_cvt_pk_bf16_f32 v2, v124, v125
	v_cvt_pk_bf16_f32 v3, v122, v123
	v_cvt_pk_bf16_f32 v4, v48, v49
	v_cvt_pk_bf16_f32 v5, v46, v47
	v_lshl_add_u64 v[10:11], v[10:11], 0, v[250:251]
	global_store_dwordx4 v[10:11], v[2:5], off
	v_pk_mul_f32 v[130:131], v[142:143], v[130:131]
	v_pk_mul_f32 v[132:133], v[144:145], v[132:133]
	v_cvt_pk_bf16_f32 v2, v128, v129
	v_cvt_pk_bf16_f32 v3, v126, v127
	v_cvt_pk_bf16_f32 v4, v52, v53
	v_cvt_pk_bf16_f32 v5, v50, v51
	v_pk_mul_f32 v[54:55], v[74:75], v[54:55]
	v_pk_mul_f32 v[56:57], v[76:77], v[56:57]
	global_store_dwordx4 v[10:11], v[2:5], off offset:2048
	s_mov_b64 s[10:11], -1
	s_nop 0
	v_cvt_pk_bf16_f32 v2, v132, v133
	v_cvt_pk_bf16_f32 v3, v130, v131
	v_cvt_pk_bf16_f32 v4, v56, v57
	v_cvt_pk_bf16_f32 v5, v54, v55
	v_lshl_add_u64 v[10:11], v[10:11], 0, v[250:251]
	global_store_dwordx4 v[10:11], v[2:5], off
	s_nop 1
	v_cvt_pk_bf16_f32 v2, v40, v41
	v_cvt_pk_bf16_f32 v3, v38, v39
	v_cvt_pk_bf16_f32 v4, v8, v9
	v_cvt_pk_bf16_f32 v5, v6, v7
	global_store_dwordx4 v[10:11], v[2:5], off offset:2048
	s_cbranch_vccnz .LBB0_1252
	s_branch .LBB0_1251
